# v51 + GEMM K-loops: first k-step peeled with SrcC=0, per-tile accumulator zeroing (128 v_mov) deleted in all 8 GEMM phases
# speedup vs baseline: 1.0057x; 1.0027x over previous
.LBB0_147:
	s_ashr_i32 s21, s20, 31
	s_lshl_b64 s[22:23], s[20:21], 19
	s_add_u32 s22, s31, s22
	s_addc_u32 s23, s40, s23
	s_and_b64 s[24:25], s[4:5], exec
	s_cselect_b32 s21, s23, s37
	s_cselect_b32 s58, s22, s36
	s_ashr_i32 s19, s18, 31
	s_lshl_b64 s[24:25], s[18:19], 19
	s_add_u32 s24, s41, s24
	s_addc_u32 s25, s44, s25
	s_and_b64 s[42:43], s[4:5], exec
	s_cselect_b32 s19, s25, s39
	s_cselect_b32 s59, s24, s38
	s_add_u32 s36, s36, 0x40080
	s_addc_u32 s37, s37, 0
	s_add_u32 s60, s38, 0x100
	s_addc_u32 s61, s39, 0
	s_mov_b32 s62, -2
	ds_read_b128 v[150:153], v147
	ds_read_b128 v[154:157], v147 offset:1024
	ds_read_b128 v[158:161], v147 offset:2048
	ds_read_b128 v[162:165], v147 offset:3072
	ds_read_b128 v[166:169], v148
	ds_read_b128 v[170:173], v148 offset:1024
	ds_read_b128 v[174:177], v148 offset:2048
	ds_read_b128 v[178:181], v148 offset:3072
	s_add_u32 s38, s36, 0xfffc0080
	s_addc_u32 s39, s37, -1
	s_cmp_eq_u32 s62, 12
	s_cselect_b32 s43, s21, s39
	s_cselect_b32 s42, s58, s38
	s_cselect_b32 s39, s19, s61
	s_cselect_b32 s38, s59, s60
	v_lshl_add_u64 v[216:217], s[36:37], 0, v[136:137]
	s_add_i32 m0, s27, 0xc000
	ds_read_b128 v[182:185], v149
	ds_read_b128 v[186:189], v149 offset:1024
	ds_read_b128 v[190:193], v149 offset:2048
	ds_read_b128 v[196:199], v149 offset:3072
	ds_read_b128 v[200:203], v149 offset:4096
	ds_read_b128 v[204:207], v149 offset:5120
	ds_read_b128 v[208:211], v149 offset:6144
	ds_read_b128 v[212:215], v149 offset:7168
	global_load_lds_dwordx4 v[216:217], off
	v_lshl_add_u64 v[216:217], s[36:37], 0, v[138:139]
	s_add_i32 m0, s27, 0xe000
	s_nop 0
	global_load_lds_dwordx4 v[216:217], off
	s_waitcnt vmcnt(8)
	s_waitcnt lgkmcnt(0)
	s_barrier
	s_setprio 1
	s_waitcnt lgkmcnt(0)
	v_mfma_f32_16x16x32_bf16 v[124:127], v[150:153], v[182:185], 0
	v_mfma_f32_16x16x32_bf16 v[120:123], v[158:161], v[182:185], 0
	v_mfma_f32_16x16x32_bf16 v[108:111], v[150:153], v[190:193], 0
	v_mfma_f32_16x16x32_bf16 v[104:107], v[158:161], v[190:193], 0
	v_mfma_f32_16x16x32_bf16 v[92:95], v[150:153], v[200:203], 0
	v_mfma_f32_16x16x32_bf16 v[88:91], v[158:161], v[200:203], 0
	v_mfma_f32_16x16x32_bf16 v[76:79], v[150:153], v[208:211], 0
	v_mfma_f32_16x16x32_bf16 v[72:75], v[158:161], v[208:211], 0
	v_mfma_f32_16x16x32_bf16 v[124:127], v[154:157], v[186:189], v[124:127]
	v_mfma_f32_16x16x32_bf16 v[120:123], v[162:165], v[186:189], v[120:123]
	v_mfma_f32_16x16x32_bf16 v[108:111], v[154:157], v[196:199], v[108:111]
	v_mfma_f32_16x16x32_bf16 v[104:107], v[162:165], v[196:199], v[104:107]
	v_mfma_f32_16x16x32_bf16 v[92:95], v[154:157], v[204:207], v[92:95]
	v_mfma_f32_16x16x32_bf16 v[88:91], v[162:165], v[204:207], v[88:91]
	v_mfma_f32_16x16x32_bf16 v[76:79], v[154:157], v[212:215], v[76:79]
	v_mfma_f32_16x16x32_bf16 v[72:75], v[162:165], v[212:215], v[72:75]
	s_setprio 0
	s_setprio 1
	v_mfma_f32_16x16x32_bf16 v[116:119], v[166:169], v[182:185], 0
	v_mfma_f32_16x16x32_bf16 v[112:115], v[174:177], v[182:185], 0
	v_mfma_f32_16x16x32_bf16 v[100:103], v[166:169], v[190:193], 0
	v_mfma_f32_16x16x32_bf16 v[96:99], v[174:177], v[190:193], 0
	v_mfma_f32_16x16x32_bf16 v[84:87], v[166:169], v[200:203], 0
	v_mfma_f32_16x16x32_bf16 v[80:83], v[174:177], v[200:203], 0
	v_mfma_f32_16x16x32_bf16 v[68:71], v[166:169], v[208:211], 0
	v_mfma_f32_16x16x32_bf16 v[64:67], v[174:177], v[208:211], 0
	v_mfma_f32_16x16x32_bf16 v[116:119], v[170:173], v[186:189], v[116:119]
	v_mfma_f32_16x16x32_bf16 v[112:115], v[178:181], v[186:189], v[112:115]
	v_mfma_f32_16x16x32_bf16 v[100:103], v[170:173], v[196:199], v[100:103]
	v_mfma_f32_16x16x32_bf16 v[96:99], v[178:181], v[196:199], v[96:99]
	v_mfma_f32_16x16x32_bf16 v[84:87], v[170:173], v[204:207], v[84:87]
	v_mfma_f32_16x16x32_bf16 v[80:83], v[178:181], v[204:207], v[80:83]
	v_mfma_f32_16x16x32_bf16 v[68:71], v[170:173], v[212:215], v[68:71]
	v_mfma_f32_16x16x32_bf16 v[64:67], v[178:181], v[212:215], v[64:67]
	s_setprio 0
	s_barrier
	s_add_i32 s63, s54, s45
	v_lshl_add_u64 v[216:217], s[38:39], 0, v[130:131]
	s_mov_b32 m0, s63
	ds_read_b128 v[182:185], v149 offset:16384
	ds_read_b128 v[186:189], v149 offset:17408
	ds_read_b128 v[190:193], v149 offset:18432
	ds_read_b128 v[196:199], v149 offset:19456
	ds_read_b128 v[200:203], v149 offset:20480
	ds_read_b128 v[204:207], v149 offset:21504
	ds_read_b128 v[208:211], v149 offset:22528
	ds_read_b128 v[212:215], v149 offset:23552
	global_load_lds_dwordx4 v[216:217], off
	s_add_i32 m0, s63, 0x2000
	s_add_u32 s64, s38, 0x40000
	v_lshl_add_u64 v[218:219], s[38:39], 0, v[134:135]
	s_addc_u32 s65, s39, 0
	s_add_i32 s63, s55, s45
	global_load_lds_dwordx4 v[218:219], off
	v_lshl_add_u64 v[220:221], s[64:65], 0, v[130:131]
	s_mov_b32 m0, s63
	v_lshl_add_u64 v[222:223], s[42:43], 0, v[132:133]
	global_load_lds_dwordx4 v[220:221], off
	v_lshl_add_u64 v[220:221], s[64:65], 0, v[134:135]
	s_add_i32 m0, s63, 0x2000
	s_nop 0
	global_load_lds_dwordx4 v[220:221], off
	v_lshl_add_u64 v[220:221], s[42:43], 0, v[128:129]
	s_mov_b32 m0, s27
	s_nop 0
	global_load_lds_dwordx4 v[220:221], off
	s_mov_b32 m0, s46
	s_nop 0
	global_load_lds_dwordx4 v[222:223], off
	s_waitcnt vmcnt(8)
	s_waitcnt lgkmcnt(0)
	s_barrier
	s_setprio 1
	s_waitcnt lgkmcnt(0)
	v_mfma_f32_16x16x32_bf16 v[60:63], v[150:153], v[182:185], 0
	v_mfma_f32_16x16x32_bf16 v[56:59], v[158:161], v[182:185], 0
	v_mfma_f32_16x16x32_bf16 v[44:47], v[150:153], v[190:193], 0
	v_mfma_f32_16x16x32_bf16 v[40:43], v[158:161], v[190:193], 0
	v_mfma_f32_16x16x32_bf16 v[28:31], v[150:153], v[200:203], 0
	v_mfma_f32_16x16x32_bf16 v[24:27], v[158:161], v[200:203], 0
	v_mfma_f32_16x16x32_bf16 v[12:15], v[150:153], v[208:211], 0
	v_mfma_f32_16x16x32_bf16 v[8:11], v[158:161], v[208:211], 0
	v_mfma_f32_16x16x32_bf16 v[60:63], v[154:157], v[186:189], v[60:63]
	v_mfma_f32_16x16x32_bf16 v[56:59], v[162:165], v[186:189], v[56:59]
	v_mfma_f32_16x16x32_bf16 v[44:47], v[154:157], v[196:199], v[44:47]
	v_mfma_f32_16x16x32_bf16 v[40:43], v[162:165], v[196:199], v[40:43]
	v_mfma_f32_16x16x32_bf16 v[28:31], v[154:157], v[204:207], v[28:31]
	v_mfma_f32_16x16x32_bf16 v[24:27], v[162:165], v[204:207], v[24:27]
	v_mfma_f32_16x16x32_bf16 v[12:15], v[154:157], v[212:215], v[12:15]
	v_mfma_f32_16x16x32_bf16 v[8:11], v[162:165], v[212:215], v[8:11]
	s_setprio 0
	s_setprio 1
	v_mfma_f32_16x16x32_bf16 v[52:55], v[166:169], v[182:185], 0
	v_mfma_f32_16x16x32_bf16 v[48:51], v[174:177], v[182:185], 0
	v_mfma_f32_16x16x32_bf16 v[36:39], v[166:169], v[190:193], 0
	v_mfma_f32_16x16x32_bf16 v[32:35], v[174:177], v[190:193], 0
	v_mfma_f32_16x16x32_bf16 v[20:23], v[166:169], v[200:203], 0
	v_mfma_f32_16x16x32_bf16 v[16:19], v[174:177], v[200:203], 0
	v_mfma_f32_16x16x32_bf16 v[4:7], v[166:169], v[208:211], 0
	v_mfma_f32_16x16x32_bf16 v[0:3], v[174:177], v[208:211], 0
	v_mfma_f32_16x16x32_bf16 v[52:55], v[170:173], v[186:189], v[52:55]
	v_mfma_f32_16x16x32_bf16 v[48:51], v[178:181], v[186:189], v[48:51]
	v_mfma_f32_16x16x32_bf16 v[36:39], v[170:173], v[196:199], v[36:39]
	v_mfma_f32_16x16x32_bf16 v[32:35], v[178:181], v[196:199], v[32:35]
	v_mfma_f32_16x16x32_bf16 v[20:23], v[170:173], v[204:207], v[20:23]
	v_mfma_f32_16x16x32_bf16 v[16:19], v[178:181], v[204:207], v[16:19]
	v_mfma_f32_16x16x32_bf16 v[4:7], v[170:173], v[212:215], v[4:7]
	v_mfma_f32_16x16x32_bf16 v[0:3], v[178:181], v[212:215], v[0:3]
	s_setprio 0
	s_barrier
	s_add_i32 s63, 0, 0x18000
	s_add_i32 s64, 0, 0x1c000
	v_add_u32_e32 v162, s63, v145
	v_add_u32_e32 v178, s64, v145
	ds_read_b128 v[150:153], v162
	ds_read_b128 v[154:157], v162 offset:1024
	ds_read_b128 v[158:161], v162 offset:2048
	ds_read_b128 v[162:165], v162 offset:3072
	ds_read_b128 v[166:169], v178
	ds_read_b128 v[170:173], v178 offset:1024
	ds_read_b128 v[174:177], v178 offset:2048
	ds_read_b128 v[178:181], v178 offset:3072
	s_add_u32 s42, s42, 0x40000
	s_addc_u32 s43, s43, 0
	s_mov_b32 m0, s47
	v_lshl_add_u64 v[224:225], s[42:43], 0, v[128:129]
	ds_read_b128 v[182:185], v149 offset:32768
	ds_read_b128 v[186:189], v149 offset:33792
	ds_read_b128 v[190:193], v149 offset:34816
	ds_read_b128 v[196:199], v149 offset:35840
	ds_read_b128 v[200:203], v149 offset:36864
	ds_read_b128 v[204:207], v149 offset:37888
	ds_read_b128 v[208:211], v149 offset:38912
	ds_read_b128 v[212:215], v149 offset:39936
	global_load_lds_dwordx4 v[224:225], off
	v_lshl_add_u64 v[224:225], s[42:43], 0, v[132:133]
	s_mov_b32 m0, s48
	s_nop 0
	global_load_lds_dwordx4 v[224:225], off
	s_waitcnt vmcnt(8)
	s_waitcnt lgkmcnt(0)
	s_barrier
	s_setprio 1
	s_waitcnt lgkmcnt(0)
	v_mfma_f32_16x16x32_bf16 v[124:127], v[150:153], v[182:185], v[124:127]
	v_mfma_f32_16x16x32_bf16 v[120:123], v[158:161], v[182:185], v[120:123]
	v_mfma_f32_16x16x32_bf16 v[108:111], v[150:153], v[190:193], v[108:111]
	v_mfma_f32_16x16x32_bf16 v[104:107], v[158:161], v[190:193], v[104:107]
	v_mfma_f32_16x16x32_bf16 v[92:95], v[150:153], v[200:203], v[92:95]
	v_mfma_f32_16x16x32_bf16 v[88:91], v[158:161], v[200:203], v[88:91]
	v_mfma_f32_16x16x32_bf16 v[76:79], v[150:153], v[208:211], v[76:79]
	v_mfma_f32_16x16x32_bf16 v[72:75], v[158:161], v[208:211], v[72:75]
	v_mfma_f32_16x16x32_bf16 v[124:127], v[154:157], v[186:189], v[124:127]
	v_mfma_f32_16x16x32_bf16 v[120:123], v[162:165], v[186:189], v[120:123]
	v_mfma_f32_16x16x32_bf16 v[108:111], v[154:157], v[196:199], v[108:111]
	v_mfma_f32_16x16x32_bf16 v[104:107], v[162:165], v[196:199], v[104:107]
	v_mfma_f32_16x16x32_bf16 v[92:95], v[154:157], v[204:207], v[92:95]
	v_mfma_f32_16x16x32_bf16 v[88:91], v[162:165], v[204:207], v[88:91]
	v_mfma_f32_16x16x32_bf16 v[76:79], v[154:157], v[212:215], v[76:79]
	v_mfma_f32_16x16x32_bf16 v[72:75], v[162:165], v[212:215], v[72:75]
	s_setprio 0
	s_setprio 1
	v_mfma_f32_16x16x32_bf16 v[116:119], v[166:169], v[182:185], v[116:119]
	v_mfma_f32_16x16x32_bf16 v[112:115], v[174:177], v[182:185], v[112:115]
	v_mfma_f32_16x16x32_bf16 v[100:103], v[166:169], v[190:193], v[100:103]
	v_mfma_f32_16x16x32_bf16 v[96:99], v[174:177], v[190:193], v[96:99]
	v_mfma_f32_16x16x32_bf16 v[84:87], v[166:169], v[200:203], v[84:87]
	v_mfma_f32_16x16x32_bf16 v[80:83], v[174:177], v[200:203], v[80:83]
	v_mfma_f32_16x16x32_bf16 v[68:71], v[166:169], v[208:211], v[68:71]
	v_mfma_f32_16x16x32_bf16 v[64:67], v[174:177], v[208:211], v[64:67]
	v_mfma_f32_16x16x32_bf16 v[116:119], v[170:173], v[186:189], v[116:119]
	v_mfma_f32_16x16x32_bf16 v[112:115], v[178:181], v[186:189], v[112:115]
	v_mfma_f32_16x16x32_bf16 v[100:103], v[170:173], v[196:199], v[100:103]
	v_mfma_f32_16x16x32_bf16 v[96:99], v[178:181], v[196:199], v[96:99]
	v_mfma_f32_16x16x32_bf16 v[84:87], v[170:173], v[204:207], v[84:87]
	v_mfma_f32_16x16x32_bf16 v[80:83], v[178:181], v[204:207], v[80:83]
	v_mfma_f32_16x16x32_bf16 v[68:71], v[170:173], v[212:215], v[68:71]
	v_mfma_f32_16x16x32_bf16 v[64:67], v[178:181], v[212:215], v[64:67]
	s_setprio 0
	s_barrier
	s_add_i32 s42, s63, s45
	v_lshl_add_u64 v[216:217], v[216:217], 0, s[14:15]
	s_mov_b32 m0, s42
	ds_read_b128 v[182:185], v149 offset:49152
	ds_read_b128 v[186:189], v149 offset:50176
	ds_read_b128 v[190:193], v149 offset:51200
	ds_read_b128 v[196:199], v149 offset:52224
	ds_read_b128 v[200:203], v149 offset:53248
	ds_read_b128 v[204:207], v149 offset:54272
	ds_read_b128 v[208:211], v149 offset:55296
	ds_read_b128 v[212:215], v149 offset:56320
	global_load_lds_dwordx4 v[216:217], off
	s_add_i32 m0, s42, 0x2000
	s_add_u32 s38, s38, 0x40080
	v_lshl_add_u64 v[216:217], v[218:219], 0, s[14:15]
	s_addc_u32 s39, s39, 0
	s_add_i32 s42, s64, s45
	global_load_lds_dwordx4 v[216:217], off
	v_lshl_add_u64 v[216:217], s[38:39], 0, v[130:131]
	s_mov_b32 m0, s42
	s_nop 0
	global_load_lds_dwordx4 v[216:217], off
	v_lshl_add_u64 v[216:217], s[38:39], 0, v[134:135]
	s_add_i32 m0, s42, 0x2000
	s_nop 0
	global_load_lds_dwordx4 v[216:217], off
	v_lshl_add_u64 v[216:217], v[220:221], 0, s[14:15]
	s_mov_b32 m0, s50
	s_nop 0
	global_load_lds_dwordx4 v[216:217], off
	v_lshl_add_u64 v[216:217], v[222:223], 0, s[14:15]
	s_mov_b32 m0, s51
	s_nop 0
	global_load_lds_dwordx4 v[216:217], off
	s_waitcnt vmcnt(8)
	s_waitcnt lgkmcnt(0)
	s_barrier
	s_setprio 1
	s_waitcnt lgkmcnt(0)
	v_mfma_f32_16x16x32_bf16 v[60:63], v[150:153], v[182:185], v[60:63]
	v_mfma_f32_16x16x32_bf16 v[56:59], v[158:161], v[182:185], v[56:59]
	v_mfma_f32_16x16x32_bf16 v[44:47], v[150:153], v[190:193], v[44:47]
	v_mfma_f32_16x16x32_bf16 v[40:43], v[158:161], v[190:193], v[40:43]
	v_mfma_f32_16x16x32_bf16 v[28:31], v[150:153], v[200:203], v[28:31]
	v_mfma_f32_16x16x32_bf16 v[24:27], v[158:161], v[200:203], v[24:27]
	v_mfma_f32_16x16x32_bf16 v[12:15], v[150:153], v[208:211], v[12:15]
	v_mfma_f32_16x16x32_bf16 v[8:11], v[158:161], v[208:211], v[8:11]
	v_mfma_f32_16x16x32_bf16 v[60:63], v[154:157], v[186:189], v[60:63]
	v_mfma_f32_16x16x32_bf16 v[56:59], v[162:165], v[186:189], v[56:59]
	v_mfma_f32_16x16x32_bf16 v[44:47], v[154:157], v[196:199], v[44:47]
	v_mfma_f32_16x16x32_bf16 v[40:43], v[162:165], v[196:199], v[40:43]
	v_mfma_f32_16x16x32_bf16 v[28:31], v[154:157], v[204:207], v[28:31]
	v_mfma_f32_16x16x32_bf16 v[24:27], v[162:165], v[204:207], v[24:27]
	v_mfma_f32_16x16x32_bf16 v[12:15], v[154:157], v[212:215], v[12:15]
	v_mfma_f32_16x16x32_bf16 v[8:11], v[162:165], v[212:215], v[8:11]
	s_setprio 0
	s_setprio 1
	v_mfma_f32_16x16x32_bf16 v[52:55], v[166:169], v[182:185], v[52:55]
	v_mfma_f32_16x16x32_bf16 v[48:51], v[174:177], v[182:185], v[48:51]
	v_mfma_f32_16x16x32_bf16 v[36:39], v[166:169], v[190:193], v[36:39]
	v_mfma_f32_16x16x32_bf16 v[32:35], v[174:177], v[190:193], v[32:35]
	v_mfma_f32_16x16x32_bf16 v[20:23], v[166:169], v[200:203], v[20:23]
	v_mfma_f32_16x16x32_bf16 v[16:19], v[174:177], v[200:203], v[16:19]
	v_mfma_f32_16x16x32_bf16 v[4:7], v[166:169], v[208:211], v[4:7]
	v_mfma_f32_16x16x32_bf16 v[0:3], v[174:177], v[208:211], v[0:3]
	v_mfma_f32_16x16x32_bf16 v[52:55], v[170:173], v[186:189], v[52:55]
	v_mfma_f32_16x16x32_bf16 v[48:51], v[178:181], v[186:189], v[48:51]
	v_mfma_f32_16x16x32_bf16 v[36:39], v[170:173], v[196:199], v[36:39]
	v_mfma_f32_16x16x32_bf16 v[32:35], v[178:181], v[196:199], v[32:35]
	v_mfma_f32_16x16x32_bf16 v[20:23], v[170:173], v[204:207], v[20:23]
	v_mfma_f32_16x16x32_bf16 v[16:19], v[178:181], v[204:207], v[16:19]
	v_mfma_f32_16x16x32_bf16 v[4:7], v[170:173], v[212:215], v[4:7]
	v_mfma_f32_16x16x32_bf16 v[0:3], v[178:181], v[212:215], v[0:3]
	s_setprio 0
	s_barrier
	s_add_i32 s62, s62, 2
	s_add_u32 s36, s36, 0x100
	s_addc_u32 s37, s37, 0
	s_add_u32 s60, s60, 0x100
	s_addc_u32 s61, s61, 0
	s_cmp_gt_u32 s62, 13
	s_cbranch_scc0 .LBB0_148
	s_branch .Lkpeel_done_148

.Lkpeel_done_148:
	s_and_b64 vcc, exec, s[16:17]
	s_cbranch_vccz .LBB0_151
	s_barrier

.LBB0_221:
	s_add_u32 s69, s38, 0x100
	s_addc_u32 s70, s39, 0
	s_mov_b32 s71, -2
	ds_read_b128 v[128:131], v175
	ds_read_b128 v[132:135], v175 offset:1024
	ds_read_b128 v[136:139], v175 offset:2048
	ds_read_b128 v[140:143], v175 offset:3072
	ds_read_b128 v[162:165], v176
	ds_read_b128 v[166:169], v176 offset:1024
	ds_read_b128 v[178:181], v176 offset:2048
	ds_read_b128 v[182:185], v176 offset:3072
	s_add_u32 s38, s36, 0x100
	s_addc_u32 s39, s37, 0
	s_cmp_eq_u32 s71, 40
	s_cselect_b32 s45, s9, s39
	s_cselect_b32 s44, s8, s38
	s_cselect_b32 s43, s27, s70
	s_cselect_b32 s42, s26, s69
	v_lshl_add_u64 v[170:171], s[36:37], 0, v[154:155]
	s_add_i32 m0, s46, 0xc000
	ds_read_b128 v[186:189], v177
	ds_read_b128 v[190:193], v177 offset:1024
	ds_read_b128 v[196:199], v177 offset:2048
	ds_read_b128 v[200:203], v177 offset:3072
	ds_read_b128 v[204:207], v177 offset:4096
	ds_read_b128 v[208:211], v177 offset:5120
	ds_read_b128 v[212:215], v177 offset:6144
	ds_read_b128 v[216:219], v177 offset:7168
	global_load_lds_dwordx4 v[170:171], off
	v_lshl_add_u64 v[170:171], s[36:37], 0, v[156:157]
	s_add_i32 m0, s46, 0xe000
	s_nop 0
	global_load_lds_dwordx4 v[170:171], off
	s_waitcnt vmcnt(8)
	s_waitcnt lgkmcnt(0)
	s_barrier
	s_setprio 1
	s_waitcnt lgkmcnt(0)
	v_mfma_f32_16x16x32_bf16 v[124:127], v[128:131], v[186:189], 0
	v_mfma_f32_16x16x32_bf16 v[120:123], v[136:139], v[186:189], 0
	v_mfma_f32_16x16x32_bf16 v[108:111], v[128:131], v[196:199], 0
	v_mfma_f32_16x16x32_bf16 v[104:107], v[136:139], v[196:199], 0
	v_mfma_f32_16x16x32_bf16 v[92:95], v[128:131], v[204:207], 0
	v_mfma_f32_16x16x32_bf16 v[88:91], v[136:139], v[204:207], 0
	v_mfma_f32_16x16x32_bf16 v[76:79], v[128:131], v[212:215], 0
	v_mfma_f32_16x16x32_bf16 v[72:75], v[136:139], v[212:215], 0
	v_mfma_f32_16x16x32_bf16 v[124:127], v[132:135], v[190:193], v[124:127]
	v_mfma_f32_16x16x32_bf16 v[120:123], v[140:143], v[190:193], v[120:123]
	v_mfma_f32_16x16x32_bf16 v[108:111], v[132:135], v[200:203], v[108:111]
	v_mfma_f32_16x16x32_bf16 v[104:107], v[140:143], v[200:203], v[104:107]
	v_mfma_f32_16x16x32_bf16 v[92:95], v[132:135], v[208:211], v[92:95]
	v_mfma_f32_16x16x32_bf16 v[88:91], v[140:143], v[208:211], v[88:91]
	v_mfma_f32_16x16x32_bf16 v[76:79], v[132:135], v[216:219], v[76:79]
	v_mfma_f32_16x16x32_bf16 v[72:75], v[140:143], v[216:219], v[72:75]
	s_setprio 0
	s_setprio 1
	v_mfma_f32_16x16x32_bf16 v[116:119], v[162:165], v[186:189], 0
	v_mfma_f32_16x16x32_bf16 v[112:115], v[178:181], v[186:189], 0
	v_mfma_f32_16x16x32_bf16 v[100:103], v[162:165], v[196:199], 0
	v_mfma_f32_16x16x32_bf16 v[96:99], v[178:181], v[196:199], 0
	v_mfma_f32_16x16x32_bf16 v[84:87], v[162:165], v[204:207], 0
	v_mfma_f32_16x16x32_bf16 v[80:83], v[178:181], v[204:207], 0
	v_mfma_f32_16x16x32_bf16 v[68:71], v[162:165], v[212:215], 0
	v_mfma_f32_16x16x32_bf16 v[64:67], v[178:181], v[212:215], 0
	v_mfma_f32_16x16x32_bf16 v[116:119], v[166:169], v[190:193], v[116:119]
	v_mfma_f32_16x16x32_bf16 v[112:115], v[182:185], v[190:193], v[112:115]
	v_mfma_f32_16x16x32_bf16 v[100:103], v[166:169], v[200:203], v[100:103]
	v_mfma_f32_16x16x32_bf16 v[96:99], v[182:185], v[200:203], v[96:99]
	v_mfma_f32_16x16x32_bf16 v[84:87], v[166:169], v[208:211], v[84:87]
	v_mfma_f32_16x16x32_bf16 v[80:83], v[182:185], v[208:211], v[80:83]
	v_mfma_f32_16x16x32_bf16 v[68:71], v[166:169], v[216:219], v[68:71]
	v_mfma_f32_16x16x32_bf16 v[64:67], v[182:185], v[216:219], v[64:67]
	s_setprio 0
	s_barrier
	s_add_i32 s36, s58, s41
	v_lshl_add_u64 v[170:171], s[42:43], 0, v[146:147]
	s_mov_b32 m0, s36
	ds_read_b128 v[186:189], v177 offset:16384
	ds_read_b128 v[190:193], v177 offset:17408
	ds_read_b128 v[196:199], v177 offset:18432
	ds_read_b128 v[200:203], v177 offset:19456
	ds_read_b128 v[204:207], v177 offset:20480
	ds_read_b128 v[208:211], v177 offset:21504
	ds_read_b128 v[212:215], v177 offset:22528
	ds_read_b128 v[216:219], v177 offset:23552
	global_load_lds_dwordx4 v[170:171], off
	s_add_i32 m0, s36, 0x2000
	s_add_u32 s36, s42, 0xb0000
	v_lshl_add_u64 v[220:221], s[42:43], 0, v[150:151]
	s_addc_u32 s37, s43, 0
	s_add_i32 s72, s59, s41
	global_load_lds_dwordx4 v[220:221], off
	v_lshl_add_u64 v[222:223], s[36:37], 0, v[146:147]
	s_mov_b32 m0, s72
	v_lshl_add_u64 v[224:225], s[44:45], 0, v[148:149]
	global_load_lds_dwordx4 v[222:223], off
	v_lshl_add_u64 v[222:223], s[36:37], 0, v[150:151]
	s_add_i32 m0, s72, 0x2000
	s_nop 0
	global_load_lds_dwordx4 v[222:223], off
	v_lshl_add_u64 v[222:223], s[44:45], 0, v[144:145]
	s_mov_b32 m0, s46
	s_nop 0
	global_load_lds_dwordx4 v[222:223], off
	s_mov_b32 m0, s47
	s_nop 0
	global_load_lds_dwordx4 v[224:225], off
	s_waitcnt vmcnt(8)
	s_waitcnt lgkmcnt(0)
	s_barrier
	s_setprio 1
	s_waitcnt lgkmcnt(0)
	v_mfma_f32_16x16x32_bf16 v[60:63], v[128:131], v[186:189], 0
	v_mfma_f32_16x16x32_bf16 v[56:59], v[136:139], v[186:189], 0
	v_mfma_f32_16x16x32_bf16 v[44:47], v[128:131], v[196:199], 0
	v_mfma_f32_16x16x32_bf16 v[40:43], v[136:139], v[196:199], 0
	v_mfma_f32_16x16x32_bf16 v[28:31], v[128:131], v[204:207], 0
	v_mfma_f32_16x16x32_bf16 v[24:27], v[136:139], v[204:207], 0
	v_mfma_f32_16x16x32_bf16 v[12:15], v[128:131], v[212:215], 0
	v_mfma_f32_16x16x32_bf16 v[8:11], v[136:139], v[212:215], 0
	v_mfma_f32_16x16x32_bf16 v[60:63], v[132:135], v[190:193], v[60:63]
	v_mfma_f32_16x16x32_bf16 v[56:59], v[140:143], v[190:193], v[56:59]
	v_mfma_f32_16x16x32_bf16 v[44:47], v[132:135], v[200:203], v[44:47]
	v_mfma_f32_16x16x32_bf16 v[40:43], v[140:143], v[200:203], v[40:43]
	v_mfma_f32_16x16x32_bf16 v[28:31], v[132:135], v[208:211], v[28:31]
	v_mfma_f32_16x16x32_bf16 v[24:27], v[140:143], v[208:211], v[24:27]
	v_mfma_f32_16x16x32_bf16 v[12:15], v[132:135], v[216:219], v[12:15]
	v_mfma_f32_16x16x32_bf16 v[8:11], v[140:143], v[216:219], v[8:11]
	s_setprio 0
	s_setprio 1
	v_mfma_f32_16x16x32_bf16 v[52:55], v[162:165], v[186:189], 0
	v_mfma_f32_16x16x32_bf16 v[48:51], v[178:181], v[186:189], 0
	v_mfma_f32_16x16x32_bf16 v[36:39], v[162:165], v[196:199], 0
	v_mfma_f32_16x16x32_bf16 v[32:35], v[178:181], v[196:199], 0
	v_mfma_f32_16x16x32_bf16 v[20:23], v[162:165], v[204:207], 0
	v_mfma_f32_16x16x32_bf16 v[16:19], v[178:181], v[204:207], 0
	v_mfma_f32_16x16x32_bf16 v[4:7], v[162:165], v[212:215], 0
	v_mfma_f32_16x16x32_bf16 v[0:3], v[178:181], v[212:215], 0
	v_mfma_f32_16x16x32_bf16 v[52:55], v[166:169], v[190:193], v[52:55]
	v_mfma_f32_16x16x32_bf16 v[48:51], v[182:185], v[190:193], v[48:51]
	v_mfma_f32_16x16x32_bf16 v[36:39], v[166:169], v[200:203], v[36:39]
	v_mfma_f32_16x16x32_bf16 v[32:35], v[182:185], v[200:203], v[32:35]
	v_mfma_f32_16x16x32_bf16 v[20:23], v[166:169], v[208:211], v[20:23]
	v_mfma_f32_16x16x32_bf16 v[16:19], v[182:185], v[208:211], v[16:19]
	v_mfma_f32_16x16x32_bf16 v[4:7], v[166:169], v[216:219], v[4:7]
	v_mfma_f32_16x16x32_bf16 v[0:3], v[182:185], v[216:219], v[0:3]
	s_setprio 0
	s_barrier
	s_add_i32 s72, 0, 0x18000
	s_add_i32 s73, 0, 0x1c000
	v_add_u32_e32 v140, s72, v173
	v_add_u32_e32 v152, s73, v173
	ds_read_b128 v[128:131], v140
	ds_read_b128 v[132:135], v140 offset:1024
	ds_read_b128 v[136:139], v140 offset:2048
	ds_read_b128 v[140:143], v140 offset:3072
	ds_read_b128 v[162:165], v152
	ds_read_b128 v[166:169], v152 offset:1024
	ds_read_b128 v[178:181], v152 offset:2048
	ds_read_b128 v[182:185], v152 offset:3072
	s_add_u32 s36, s44, 0xb0000
	s_addc_u32 s37, s45, 0
	s_mov_b32 m0, s48
	v_lshl_add_u64 v[226:227], s[36:37], 0, v[144:145]
	ds_read_b128 v[186:189], v177 offset:32768
	ds_read_b128 v[190:193], v177 offset:33792
	ds_read_b128 v[196:199], v177 offset:34816
	ds_read_b128 v[200:203], v177 offset:35840
	ds_read_b128 v[204:207], v177 offset:36864
	ds_read_b128 v[208:211], v177 offset:37888
	ds_read_b128 v[212:215], v177 offset:38912
	ds_read_b128 v[216:219], v177 offset:39936
	global_load_lds_dwordx4 v[226:227], off
	v_lshl_add_u64 v[226:227], s[36:37], 0, v[148:149]
	s_mov_b32 m0, s49
	s_nop 0
	global_load_lds_dwordx4 v[226:227], off
	s_waitcnt vmcnt(8)
	s_waitcnt lgkmcnt(0)
	s_barrier
	s_setprio 1
	s_waitcnt lgkmcnt(0)
	v_mfma_f32_16x16x32_bf16 v[124:127], v[128:131], v[186:189], v[124:127]
	v_mfma_f32_16x16x32_bf16 v[120:123], v[136:139], v[186:189], v[120:123]
	v_mfma_f32_16x16x32_bf16 v[108:111], v[128:131], v[196:199], v[108:111]
	v_mfma_f32_16x16x32_bf16 v[104:107], v[136:139], v[196:199], v[104:107]
	v_mfma_f32_16x16x32_bf16 v[92:95], v[128:131], v[204:207], v[92:95]
	v_mfma_f32_16x16x32_bf16 v[88:91], v[136:139], v[204:207], v[88:91]
	v_mfma_f32_16x16x32_bf16 v[76:79], v[128:131], v[212:215], v[76:79]
	v_mfma_f32_16x16x32_bf16 v[72:75], v[136:139], v[212:215], v[72:75]
	v_mfma_f32_16x16x32_bf16 v[124:127], v[132:135], v[190:193], v[124:127]
	v_mfma_f32_16x16x32_bf16 v[120:123], v[140:143], v[190:193], v[120:123]
	v_mfma_f32_16x16x32_bf16 v[108:111], v[132:135], v[200:203], v[108:111]
	v_mfma_f32_16x16x32_bf16 v[104:107], v[140:143], v[200:203], v[104:107]
	v_mfma_f32_16x16x32_bf16 v[92:95], v[132:135], v[208:211], v[92:95]
	v_mfma_f32_16x16x32_bf16 v[88:91], v[140:143], v[208:211], v[88:91]
	v_mfma_f32_16x16x32_bf16 v[76:79], v[132:135], v[216:219], v[76:79]
	v_mfma_f32_16x16x32_bf16 v[72:75], v[140:143], v[216:219], v[72:75]
	s_setprio 0
	s_setprio 1
	v_mfma_f32_16x16x32_bf16 v[116:119], v[162:165], v[186:189], v[116:119]
	v_mfma_f32_16x16x32_bf16 v[112:115], v[178:181], v[186:189], v[112:115]
	v_mfma_f32_16x16x32_bf16 v[100:103], v[162:165], v[196:199], v[100:103]
	v_mfma_f32_16x16x32_bf16 v[96:99], v[178:181], v[196:199], v[96:99]
	v_mfma_f32_16x16x32_bf16 v[84:87], v[162:165], v[204:207], v[84:87]
	v_mfma_f32_16x16x32_bf16 v[80:83], v[178:181], v[204:207], v[80:83]
	v_mfma_f32_16x16x32_bf16 v[68:71], v[162:165], v[212:215], v[68:71]
	v_mfma_f32_16x16x32_bf16 v[64:67], v[178:181], v[212:215], v[64:67]
	v_mfma_f32_16x16x32_bf16 v[116:119], v[166:169], v[190:193], v[116:119]
	v_mfma_f32_16x16x32_bf16 v[112:115], v[182:185], v[190:193], v[112:115]
	v_mfma_f32_16x16x32_bf16 v[100:103], v[166:169], v[200:203], v[100:103]
	v_mfma_f32_16x16x32_bf16 v[96:99], v[182:185], v[200:203], v[96:99]
	v_mfma_f32_16x16x32_bf16 v[84:87], v[166:169], v[208:211], v[84:87]
	v_mfma_f32_16x16x32_bf16 v[80:83], v[182:185], v[208:211], v[80:83]
	v_mfma_f32_16x16x32_bf16 v[68:71], v[166:169], v[216:219], v[68:71]
	v_mfma_f32_16x16x32_bf16 v[64:67], v[182:185], v[216:219], v[64:67]
	s_setprio 0
	s_barrier
	s_add_i32 s36, s72, s41
	v_lshl_add_u64 v[170:171], v[170:171], 0, s[20:21]
	s_mov_b32 m0, s36
	ds_read_b128 v[186:189], v177 offset:49152
	ds_read_b128 v[190:193], v177 offset:50176
	ds_read_b128 v[196:199], v177 offset:51200
	ds_read_b128 v[200:203], v177 offset:52224
	ds_read_b128 v[204:207], v177 offset:53248
	ds_read_b128 v[208:211], v177 offset:54272
	ds_read_b128 v[212:215], v177 offset:55296
	ds_read_b128 v[216:219], v177 offset:56320
	global_load_lds_dwordx4 v[170:171], off
	s_add_i32 m0, s36, 0x2000
	s_add_u32 s36, s42, 0xb0080
	v_lshl_add_u64 v[170:171], v[220:221], 0, s[20:21]
	s_addc_u32 s37, s43, 0
	s_add_i32 s42, s73, s41
	global_load_lds_dwordx4 v[170:171], off
	v_lshl_add_u64 v[170:171], s[36:37], 0, v[146:147]
	s_mov_b32 m0, s42
	s_nop 0
	global_load_lds_dwordx4 v[170:171], off
	v_lshl_add_u64 v[170:171], s[36:37], 0, v[150:151]
	s_add_i32 m0, s42, 0x2000
	s_nop 0
	global_load_lds_dwordx4 v[170:171], off
	v_lshl_add_u64 v[170:171], v[222:223], 0, s[20:21]
	s_mov_b32 m0, s52
	s_nop 0
	global_load_lds_dwordx4 v[170:171], off
	v_lshl_add_u64 v[170:171], v[224:225], 0, s[20:21]
	s_mov_b32 m0, s53
	s_nop 0
	global_load_lds_dwordx4 v[170:171], off
	s_waitcnt vmcnt(8)
	s_waitcnt lgkmcnt(0)
	s_barrier
	s_setprio 1
	s_waitcnt lgkmcnt(0)
	v_mfma_f32_16x16x32_bf16 v[60:63], v[128:131], v[186:189], v[60:63]
	v_mfma_f32_16x16x32_bf16 v[56:59], v[136:139], v[186:189], v[56:59]
	v_mfma_f32_16x16x32_bf16 v[44:47], v[128:131], v[196:199], v[44:47]
	v_mfma_f32_16x16x32_bf16 v[40:43], v[136:139], v[196:199], v[40:43]
	v_mfma_f32_16x16x32_bf16 v[28:31], v[128:131], v[204:207], v[28:31]
	v_mfma_f32_16x16x32_bf16 v[24:27], v[136:139], v[204:207], v[24:27]
	v_mfma_f32_16x16x32_bf16 v[12:15], v[128:131], v[212:215], v[12:15]
	v_mfma_f32_16x16x32_bf16 v[8:11], v[136:139], v[212:215], v[8:11]
	v_mfma_f32_16x16x32_bf16 v[60:63], v[132:135], v[190:193], v[60:63]
	v_mfma_f32_16x16x32_bf16 v[56:59], v[140:143], v[190:193], v[56:59]
	v_mfma_f32_16x16x32_bf16 v[44:47], v[132:135], v[200:203], v[44:47]
	v_mfma_f32_16x16x32_bf16 v[40:43], v[140:143], v[200:203], v[40:43]
	v_mfma_f32_16x16x32_bf16 v[28:31], v[132:135], v[208:211], v[28:31]
	v_mfma_f32_16x16x32_bf16 v[24:27], v[140:143], v[208:211], v[24:27]
	v_mfma_f32_16x16x32_bf16 v[12:15], v[132:135], v[216:219], v[12:15]
	v_mfma_f32_16x16x32_bf16 v[8:11], v[140:143], v[216:219], v[8:11]
	s_setprio 0
	s_setprio 1
	v_mfma_f32_16x16x32_bf16 v[52:55], v[162:165], v[186:189], v[52:55]
	v_mfma_f32_16x16x32_bf16 v[48:51], v[178:181], v[186:189], v[48:51]
	v_mfma_f32_16x16x32_bf16 v[36:39], v[162:165], v[196:199], v[36:39]
	v_mfma_f32_16x16x32_bf16 v[32:35], v[178:181], v[196:199], v[32:35]
	v_mfma_f32_16x16x32_bf16 v[20:23], v[162:165], v[204:207], v[20:23]
	v_mfma_f32_16x16x32_bf16 v[16:19], v[178:181], v[204:207], v[16:19]
	v_mfma_f32_16x16x32_bf16 v[4:7], v[162:165], v[212:215], v[4:7]
	v_mfma_f32_16x16x32_bf16 v[0:3], v[178:181], v[212:215], v[0:3]
	v_mfma_f32_16x16x32_bf16 v[52:55], v[166:169], v[190:193], v[52:55]
	v_mfma_f32_16x16x32_bf16 v[48:51], v[182:185], v[190:193], v[48:51]
	v_mfma_f32_16x16x32_bf16 v[36:39], v[166:169], v[200:203], v[36:39]
	v_mfma_f32_16x16x32_bf16 v[32:35], v[182:185], v[200:203], v[32:35]
	v_mfma_f32_16x16x32_bf16 v[20:23], v[166:169], v[208:211], v[20:23]
	v_mfma_f32_16x16x32_bf16 v[16:19], v[182:185], v[208:211], v[16:19]
	v_mfma_f32_16x16x32_bf16 v[4:7], v[166:169], v[216:219], v[4:7]
	v_mfma_f32_16x16x32_bf16 v[0:3], v[182:185], v[216:219], v[0:3]
	s_setprio 0
	s_barrier
	s_add_i32 s71, s71, 2
	s_add_u32 s69, s69, 0x100
	s_addc_u32 s70, s70, 0
	s_cmp_gt_u32 s71, 41
	s_mov_b64 s[36:37], s[38:39]
	s_cbranch_scc0 .LBB0_222
	s_branch .Lkpeel_done_222

.Lkpeel_done_222:
	s_and_b64 vcc, exec, s[22:23]
	s_cbranch_vccz .LBB0_225
	s_barrier

.LBB0_370:
	s_ashr_i32 s51, s50, 31
	s_lshl_b64 s[18:19], s[50:51], 19
	s_add_u32 s52, s3, s18
	s_addc_u32 s53, s31, s19
	s_and_b64 s[18:19], s[8:9], exec
	s_cselect_b32 s13, s53, s11
	s_cselect_b32 s15, s52, s10
	s_ashr_i32 s49, s48, 31
	s_lshl_b64 s[18:19], s[48:49], 19
	s_add_u32 s54, s76, s18
	s_addc_u32 s55, s77, s19
	s_and_b64 s[18:19], s[8:9], exec
	s_cselect_b32 s24, s55, s17
	s_cselect_b32 s49, s54, s16
	s_add_u32 s10, s10, 0x40080
	s_addc_u32 s11, s11, 0
	s_add_u32 s51, s16, 0x100
	s_addc_u32 s56, s17, 0
	s_mov_b32 s57, -2
	ds_read_b128 v[128:131], v184
	ds_read_b128 v[132:135], v184 offset:1024
	ds_read_b128 v[174:177], v184 offset:2048
	ds_read_b128 v[178:181], v184 offset:3072
	ds_read_b128 v[188:191], v185
	ds_read_b128 v[196:199], v185 offset:1024
	ds_read_b128 v[200:203], v185 offset:2048
	ds_read_b128 v[204:207], v185 offset:3072
	s_add_u32 s16, s10, 0xfffc0080
	s_addc_u32 s17, s11, -1
	s_cmp_eq_u32 s57, 12
	s_cselect_b32 s19, s13, s17
	s_cselect_b32 s18, s15, s16
	s_cselect_b32 s17, s24, s56
	s_cselect_b32 s16, s49, s51
	v_lshl_add_u64 v[192:193], s[10:11], 0, v[166:167]
	s_add_i32 m0, s79, 0xc000
	ds_read_b128 v[208:211], v186
	ds_read_b128 v[212:215], v186 offset:1024
	ds_read_b128 v[216:219], v186 offset:2048
	ds_read_b128 v[220:223], v186 offset:3072
	ds_read_b128 v[224:227], v186 offset:4096
	ds_read_b128 v[228:231], v186 offset:5120
	ds_read_b128 v[232:235], v186 offset:6144
	ds_read_b128 v[236:239], v186 offset:7168
	global_load_lds_dwordx4 v[192:193], off
	v_lshl_add_u64 v[192:193], s[10:11], 0, v[168:169]
	s_add_i32 m0, s79, 0xe000
	s_nop 0
	global_load_lds_dwordx4 v[192:193], off
	s_waitcnt vmcnt(8)
	s_waitcnt lgkmcnt(0)
	s_barrier
	s_setprio 1
	s_waitcnt lgkmcnt(0)
	v_mfma_f32_16x16x32_bf16 v[124:127], v[128:131], v[208:211], 0
	v_mfma_f32_16x16x32_bf16 v[120:123], v[174:177], v[208:211], 0
	v_mfma_f32_16x16x32_bf16 v[108:111], v[128:131], v[216:219], 0
	v_mfma_f32_16x16x32_bf16 v[104:107], v[174:177], v[216:219], 0
	v_mfma_f32_16x16x32_bf16 v[92:95], v[128:131], v[224:227], 0
	v_mfma_f32_16x16x32_bf16 v[88:91], v[174:177], v[224:227], 0
	v_mfma_f32_16x16x32_bf16 v[76:79], v[128:131], v[232:235], 0
	v_mfma_f32_16x16x32_bf16 v[72:75], v[174:177], v[232:235], 0
	v_mfma_f32_16x16x32_bf16 v[124:127], v[132:135], v[212:215], v[124:127]
	v_mfma_f32_16x16x32_bf16 v[120:123], v[178:181], v[212:215], v[120:123]
	v_mfma_f32_16x16x32_bf16 v[108:111], v[132:135], v[220:223], v[108:111]
	v_mfma_f32_16x16x32_bf16 v[104:107], v[178:181], v[220:223], v[104:107]
	v_mfma_f32_16x16x32_bf16 v[92:95], v[132:135], v[228:231], v[92:95]
	v_mfma_f32_16x16x32_bf16 v[88:91], v[178:181], v[228:231], v[88:91]
	v_mfma_f32_16x16x32_bf16 v[76:79], v[132:135], v[236:239], v[76:79]
	v_mfma_f32_16x16x32_bf16 v[72:75], v[178:181], v[236:239], v[72:75]
	s_setprio 0
	s_setprio 1
	v_mfma_f32_16x16x32_bf16 v[116:119], v[188:191], v[208:211], 0
	v_mfma_f32_16x16x32_bf16 v[112:115], v[200:203], v[208:211], 0
	v_mfma_f32_16x16x32_bf16 v[100:103], v[188:191], v[216:219], 0
	v_mfma_f32_16x16x32_bf16 v[96:99], v[200:203], v[216:219], 0
	v_mfma_f32_16x16x32_bf16 v[84:87], v[188:191], v[224:227], 0
	v_mfma_f32_16x16x32_bf16 v[80:83], v[200:203], v[224:227], 0
	v_mfma_f32_16x16x32_bf16 v[68:71], v[188:191], v[232:235], 0
	v_mfma_f32_16x16x32_bf16 v[64:67], v[200:203], v[232:235], 0
	v_mfma_f32_16x16x32_bf16 v[116:119], v[196:199], v[212:215], v[116:119]
	v_mfma_f32_16x16x32_bf16 v[112:115], v[204:207], v[212:215], v[112:115]
	v_mfma_f32_16x16x32_bf16 v[100:103], v[196:199], v[220:223], v[100:103]
	v_mfma_f32_16x16x32_bf16 v[96:99], v[204:207], v[220:223], v[96:99]
	v_mfma_f32_16x16x32_bf16 v[84:87], v[196:199], v[228:231], v[84:87]
	v_mfma_f32_16x16x32_bf16 v[80:83], v[204:207], v[228:231], v[80:83]
	v_mfma_f32_16x16x32_bf16 v[68:71], v[196:199], v[236:239], v[68:71]
	v_mfma_f32_16x16x32_bf16 v[64:67], v[204:207], v[236:239], v[64:67]
	s_setprio 0
	s_barrier
	s_add_i32 s58, s88, s78
	v_lshl_add_u64 v[192:193], s[16:17], 0, v[138:139]
	s_mov_b32 m0, s58
	ds_read_b128 v[208:211], v186 offset:16384
	ds_read_b128 v[212:215], v186 offset:17408
	ds_read_b128 v[216:219], v186 offset:18432
	ds_read_b128 v[220:223], v186 offset:19456
	ds_read_b128 v[224:227], v186 offset:20480
	ds_read_b128 v[228:231], v186 offset:21504
	ds_read_b128 v[232:235], v186 offset:22528
	ds_read_b128 v[236:239], v186 offset:23552
	global_load_lds_dwordx4 v[192:193], off
	s_add_i32 m0, s58, 0x2000
	s_add_u32 s58, s16, 0x40000
	v_lshl_add_u64 v[240:241], s[16:17], 0, v[142:143]
	s_addc_u32 s59, s17, 0
	s_add_i32 s60, s89, s78
	global_load_lds_dwordx4 v[240:241], off
	v_lshl_add_u64 v[242:243], s[58:59], 0, v[138:139]
	s_mov_b32 m0, s60
	v_lshl_add_u64 v[244:245], s[18:19], 0, v[140:141]
	global_load_lds_dwordx4 v[242:243], off
	v_lshl_add_u64 v[242:243], s[58:59], 0, v[142:143]
	s_add_i32 m0, s60, 0x2000
	s_nop 0
	global_load_lds_dwordx4 v[242:243], off
	v_lshl_add_u64 v[242:243], s[18:19], 0, v[136:137]
	s_mov_b32 m0, s79
	s_nop 0
	global_load_lds_dwordx4 v[242:243], off
	s_mov_b32 m0, s80
	s_nop 0
	global_load_lds_dwordx4 v[244:245], off
	s_waitcnt vmcnt(8)
	s_waitcnt lgkmcnt(0)
	s_barrier
	s_setprio 1
	s_waitcnt lgkmcnt(0)
	v_mfma_f32_16x16x32_bf16 v[60:63], v[128:131], v[208:211], 0
	v_mfma_f32_16x16x32_bf16 v[56:59], v[174:177], v[208:211], 0
	v_mfma_f32_16x16x32_bf16 v[44:47], v[128:131], v[216:219], 0
	v_mfma_f32_16x16x32_bf16 v[40:43], v[174:177], v[216:219], 0
	v_mfma_f32_16x16x32_bf16 v[28:31], v[128:131], v[224:227], 0
	v_mfma_f32_16x16x32_bf16 v[24:27], v[174:177], v[224:227], 0
	v_mfma_f32_16x16x32_bf16 v[12:15], v[128:131], v[232:235], 0
	v_mfma_f32_16x16x32_bf16 v[8:11], v[174:177], v[232:235], 0
	v_mfma_f32_16x16x32_bf16 v[60:63], v[132:135], v[212:215], v[60:63]
	v_mfma_f32_16x16x32_bf16 v[56:59], v[178:181], v[212:215], v[56:59]
	v_mfma_f32_16x16x32_bf16 v[44:47], v[132:135], v[220:223], v[44:47]
	v_mfma_f32_16x16x32_bf16 v[40:43], v[178:181], v[220:223], v[40:43]
	v_mfma_f32_16x16x32_bf16 v[28:31], v[132:135], v[228:231], v[28:31]
	v_mfma_f32_16x16x32_bf16 v[24:27], v[178:181], v[228:231], v[24:27]
	v_mfma_f32_16x16x32_bf16 v[12:15], v[132:135], v[236:239], v[12:15]
	v_mfma_f32_16x16x32_bf16 v[8:11], v[178:181], v[236:239], v[8:11]
	s_setprio 0
	s_setprio 1
	v_mfma_f32_16x16x32_bf16 v[52:55], v[188:191], v[208:211], 0
	v_mfma_f32_16x16x32_bf16 v[48:51], v[200:203], v[208:211], 0
	v_mfma_f32_16x16x32_bf16 v[36:39], v[188:191], v[216:219], 0
	v_mfma_f32_16x16x32_bf16 v[32:35], v[200:203], v[216:219], 0
	v_mfma_f32_16x16x32_bf16 v[20:23], v[188:191], v[224:227], 0
	v_mfma_f32_16x16x32_bf16 v[16:19], v[200:203], v[224:227], 0
	v_mfma_f32_16x16x32_bf16 v[4:7], v[188:191], v[232:235], 0
	v_mfma_f32_16x16x32_bf16 v[0:3], v[200:203], v[232:235], 0
	v_mfma_f32_16x16x32_bf16 v[52:55], v[196:199], v[212:215], v[52:55]
	v_mfma_f32_16x16x32_bf16 v[48:51], v[204:207], v[212:215], v[48:51]
	v_mfma_f32_16x16x32_bf16 v[36:39], v[196:199], v[220:223], v[36:39]
	v_mfma_f32_16x16x32_bf16 v[32:35], v[204:207], v[220:223], v[32:35]
	v_mfma_f32_16x16x32_bf16 v[20:23], v[196:199], v[228:231], v[20:23]
	v_mfma_f32_16x16x32_bf16 v[16:19], v[204:207], v[228:231], v[16:19]
	v_mfma_f32_16x16x32_bf16 v[4:7], v[196:199], v[236:239], v[4:7]
	v_mfma_f32_16x16x32_bf16 v[0:3], v[204:207], v[236:239], v[0:3]
	s_setprio 0
	s_barrier
	s_add_i32 s58, 0, 0x18000
	v_add_u32_e32 v144, s58, v183
	s_add_i32 s59, 0, 0x1c000
	ds_read_b128 v[128:131], v144
	ds_read_b128 v[132:135], v144 offset:1024
	ds_read_b128 v[174:177], v144 offset:2048
	ds_read_b128 v[178:181], v144 offset:3072
	v_add_u32_e32 v144, s59, v183
	ds_read_b128 v[188:191], v144
	ds_read_b128 v[196:199], v144 offset:1024
	ds_read_b128 v[200:203], v144 offset:2048
	ds_read_b128 v[204:207], v144 offset:3072
	s_add_u32 s18, s18, 0x40000
	s_addc_u32 s19, s19, 0
	s_mov_b32 m0, s81
	v_lshl_add_u64 v[246:247], s[18:19], 0, v[136:137]
	ds_read_b128 v[208:211], v186 offset:32768
	ds_read_b128 v[212:215], v186 offset:33792
	ds_read_b128 v[216:219], v186 offset:34816
	ds_read_b128 v[220:223], v186 offset:35840
	ds_read_b128 v[224:227], v186 offset:36864
	ds_read_b128 v[228:231], v186 offset:37888
	ds_read_b128 v[232:235], v186 offset:38912
	ds_read_b128 v[236:239], v186 offset:39936
	global_load_lds_dwordx4 v[246:247], off
	v_lshl_add_u64 v[246:247], s[18:19], 0, v[140:141]
	s_mov_b32 m0, s82
	s_nop 0
	global_load_lds_dwordx4 v[246:247], off
	s_waitcnt vmcnt(8)
	s_waitcnt lgkmcnt(0)
	s_barrier
	s_setprio 1
	s_waitcnt lgkmcnt(0)
	v_mfma_f32_16x16x32_bf16 v[124:127], v[128:131], v[208:211], v[124:127]
	v_mfma_f32_16x16x32_bf16 v[120:123], v[174:177], v[208:211], v[120:123]
	v_mfma_f32_16x16x32_bf16 v[108:111], v[128:131], v[216:219], v[108:111]
	v_mfma_f32_16x16x32_bf16 v[104:107], v[174:177], v[216:219], v[104:107]
	v_mfma_f32_16x16x32_bf16 v[92:95], v[128:131], v[224:227], v[92:95]
	v_mfma_f32_16x16x32_bf16 v[88:91], v[174:177], v[224:227], v[88:91]
	v_mfma_f32_16x16x32_bf16 v[76:79], v[128:131], v[232:235], v[76:79]
	v_mfma_f32_16x16x32_bf16 v[72:75], v[174:177], v[232:235], v[72:75]
	v_mfma_f32_16x16x32_bf16 v[124:127], v[132:135], v[212:215], v[124:127]
	v_mfma_f32_16x16x32_bf16 v[120:123], v[178:181], v[212:215], v[120:123]
	v_mfma_f32_16x16x32_bf16 v[108:111], v[132:135], v[220:223], v[108:111]
	v_mfma_f32_16x16x32_bf16 v[104:107], v[178:181], v[220:223], v[104:107]
	v_mfma_f32_16x16x32_bf16 v[92:95], v[132:135], v[228:231], v[92:95]
	v_mfma_f32_16x16x32_bf16 v[88:91], v[178:181], v[228:231], v[88:91]
	v_mfma_f32_16x16x32_bf16 v[76:79], v[132:135], v[236:239], v[76:79]
	v_mfma_f32_16x16x32_bf16 v[72:75], v[178:181], v[236:239], v[72:75]
	s_setprio 0
	s_setprio 1
	v_mfma_f32_16x16x32_bf16 v[116:119], v[188:191], v[208:211], v[116:119]
	v_mfma_f32_16x16x32_bf16 v[112:115], v[200:203], v[208:211], v[112:115]
	v_mfma_f32_16x16x32_bf16 v[100:103], v[188:191], v[216:219], v[100:103]
	v_mfma_f32_16x16x32_bf16 v[96:99], v[200:203], v[216:219], v[96:99]
	v_mfma_f32_16x16x32_bf16 v[84:87], v[188:191], v[224:227], v[84:87]
	v_mfma_f32_16x16x32_bf16 v[80:83], v[200:203], v[224:227], v[80:83]
	v_mfma_f32_16x16x32_bf16 v[68:71], v[188:191], v[232:235], v[68:71]
	v_mfma_f32_16x16x32_bf16 v[64:67], v[200:203], v[232:235], v[64:67]
	v_mfma_f32_16x16x32_bf16 v[116:119], v[196:199], v[212:215], v[116:119]
	v_mfma_f32_16x16x32_bf16 v[112:115], v[204:207], v[212:215], v[112:115]
	v_mfma_f32_16x16x32_bf16 v[100:103], v[196:199], v[220:223], v[100:103]
	v_mfma_f32_16x16x32_bf16 v[96:99], v[204:207], v[220:223], v[96:99]
	v_mfma_f32_16x16x32_bf16 v[84:87], v[196:199], v[228:231], v[84:87]
	v_mfma_f32_16x16x32_bf16 v[80:83], v[204:207], v[228:231], v[80:83]
	v_mfma_f32_16x16x32_bf16 v[68:71], v[196:199], v[236:239], v[68:71]
	v_mfma_f32_16x16x32_bf16 v[64:67], v[204:207], v[236:239], v[64:67]
	s_setprio 0
	s_barrier
	s_add_i32 s18, s58, s78
	v_lshl_add_u64 v[192:193], v[192:193], 0, s[36:37]
	s_mov_b32 m0, s18
	ds_read_b128 v[208:211], v186 offset:49152
	ds_read_b128 v[212:215], v186 offset:50176
	ds_read_b128 v[216:219], v186 offset:51200
	ds_read_b128 v[220:223], v186 offset:52224
	ds_read_b128 v[224:227], v186 offset:53248
	ds_read_b128 v[228:231], v186 offset:54272
	ds_read_b128 v[232:235], v186 offset:55296
	ds_read_b128 v[236:239], v186 offset:56320
	global_load_lds_dwordx4 v[192:193], off
	s_add_i32 m0, s18, 0x2000
	s_add_u32 s16, s16, 0x40080
	v_lshl_add_u64 v[192:193], v[240:241], 0, s[36:37]
	s_addc_u32 s17, s17, 0
	s_add_i32 s18, s59, s78
	global_load_lds_dwordx4 v[192:193], off
	v_lshl_add_u64 v[192:193], s[16:17], 0, v[138:139]
	s_mov_b32 m0, s18
	s_nop 0
	global_load_lds_dwordx4 v[192:193], off
	v_lshl_add_u64 v[192:193], s[16:17], 0, v[142:143]
	s_add_i32 m0, s18, 0x2000
	s_nop 0
	global_load_lds_dwordx4 v[192:193], off
	v_lshl_add_u64 v[192:193], v[242:243], 0, s[36:37]
	s_mov_b32 m0, s83
	s_nop 0
	global_load_lds_dwordx4 v[192:193], off
	v_lshl_add_u64 v[192:193], v[244:245], 0, s[36:37]
	s_mov_b32 m0, s84
	s_nop 0
	global_load_lds_dwordx4 v[192:193], off
	s_waitcnt vmcnt(8)
	s_waitcnt lgkmcnt(0)
	s_barrier
	s_setprio 1
	s_waitcnt lgkmcnt(0)
	v_mfma_f32_16x16x32_bf16 v[60:63], v[128:131], v[208:211], v[60:63]
	v_mfma_f32_16x16x32_bf16 v[56:59], v[174:177], v[208:211], v[56:59]
	v_mfma_f32_16x16x32_bf16 v[44:47], v[128:131], v[216:219], v[44:47]
	v_mfma_f32_16x16x32_bf16 v[40:43], v[174:177], v[216:219], v[40:43]
	v_mfma_f32_16x16x32_bf16 v[28:31], v[128:131], v[224:227], v[28:31]
	v_mfma_f32_16x16x32_bf16 v[24:27], v[174:177], v[224:227], v[24:27]
	v_mfma_f32_16x16x32_bf16 v[12:15], v[128:131], v[232:235], v[12:15]
	v_mfma_f32_16x16x32_bf16 v[8:11], v[174:177], v[232:235], v[8:11]
	v_mfma_f32_16x16x32_bf16 v[60:63], v[132:135], v[212:215], v[60:63]
	v_mfma_f32_16x16x32_bf16 v[56:59], v[178:181], v[212:215], v[56:59]
	v_mfma_f32_16x16x32_bf16 v[44:47], v[132:135], v[220:223], v[44:47]
	v_mfma_f32_16x16x32_bf16 v[40:43], v[178:181], v[220:223], v[40:43]
	v_mfma_f32_16x16x32_bf16 v[28:31], v[132:135], v[228:231], v[28:31]
	v_mfma_f32_16x16x32_bf16 v[24:27], v[178:181], v[228:231], v[24:27]
	v_mfma_f32_16x16x32_bf16 v[12:15], v[132:135], v[236:239], v[12:15]
	v_mfma_f32_16x16x32_bf16 v[8:11], v[178:181], v[236:239], v[8:11]
	s_setprio 0
	s_setprio 1
	v_mfma_f32_16x16x32_bf16 v[52:55], v[188:191], v[208:211], v[52:55]
	v_mfma_f32_16x16x32_bf16 v[48:51], v[200:203], v[208:211], v[48:51]
	v_mfma_f32_16x16x32_bf16 v[36:39], v[188:191], v[216:219], v[36:39]
	v_mfma_f32_16x16x32_bf16 v[32:35], v[200:203], v[216:219], v[32:35]
	v_mfma_f32_16x16x32_bf16 v[20:23], v[188:191], v[224:227], v[20:23]
	v_mfma_f32_16x16x32_bf16 v[16:19], v[200:203], v[224:227], v[16:19]
	v_mfma_f32_16x16x32_bf16 v[4:7], v[188:191], v[232:235], v[4:7]
	v_mfma_f32_16x16x32_bf16 v[0:3], v[200:203], v[232:235], v[0:3]
	v_mfma_f32_16x16x32_bf16 v[52:55], v[196:199], v[212:215], v[52:55]
	v_mfma_f32_16x16x32_bf16 v[48:51], v[204:207], v[212:215], v[48:51]
	v_mfma_f32_16x16x32_bf16 v[36:39], v[196:199], v[220:223], v[36:39]
	v_mfma_f32_16x16x32_bf16 v[32:35], v[204:207], v[220:223], v[32:35]
	v_mfma_f32_16x16x32_bf16 v[20:23], v[196:199], v[228:231], v[20:23]
	v_mfma_f32_16x16x32_bf16 v[16:19], v[204:207], v[228:231], v[16:19]
	v_mfma_f32_16x16x32_bf16 v[4:7], v[196:199], v[236:239], v[4:7]
	v_mfma_f32_16x16x32_bf16 v[0:3], v[204:207], v[236:239], v[0:3]
	s_setprio 0
	s_barrier
	s_add_i32 s57, s57, 2
	s_add_u32 s10, s10, 0x100
	s_addc_u32 s11, s11, 0
	s_add_u32 s51, s51, 0x100
	s_addc_u32 s56, s56, 0
	s_cmp_gt_u32 s57, 13
	s_cbranch_scc0 .LBB0_371
	s_branch .Lkpeel_done_371

.Lkpeel_done_371:
	s_and_b64 vcc, exec, s[38:39]
	s_cbranch_vccz .LBB0_374
	s_barrier

.LBB0_1358:
	s_ashr_i32 s37, s36, 31
	s_lshl_b64 s[38:39], s[36:37], 19
	s_add_u32 s38, s3, s38
	s_addc_u32 s39, s31, s39
	s_and_b64 s[42:43], s[6:7], exec
	s_cselect_b32 s37, s39, s47
	s_cselect_b32 s66, s38, s46
	s_ashr_i32 s27, s26, 31
	s_lshl_b64 s[42:43], s[26:27], 19
	s_add_u32 s42, s40, s42
	s_addc_u32 s43, s41, s43
	s_and_b64 s[50:51], s[6:7], exec
	s_cselect_b32 s27, s43, s49
	s_cselect_b32 s67, s42, s48
	s_add_u32 s46, s46, 0x40080
	s_addc_u32 s47, s47, 0
	s_add_u32 s68, s48, 0x100
	s_addc_u32 s69, s49, 0
	s_mov_b32 s70, -2
	ds_read_b128 v[144:147], v153
	ds_read_b128 v[156:159], v153 offset:1024
	ds_read_b128 v[160:163], v153 offset:2048
	ds_read_b128 v[164:167], v153 offset:3072
	ds_read_b128 v[168:171], v154
	ds_read_b128 v[172:175], v154 offset:1024
	ds_read_b128 v[176:179], v154 offset:2048
	ds_read_b128 v[184:187], v154 offset:3072
	s_add_u32 s48, s46, 0xfffc0080
	s_addc_u32 s49, s47, -1
	s_cmp_eq_u32 s70, 12
	s_cselect_b32 s51, s37, s49
	s_cselect_b32 s50, s66, s48
	s_cselect_b32 s49, s27, s69
	s_cselect_b32 s48, s67, s68
	v_lshl_add_u64 v[148:149], s[46:47], 0, v[136:137]
	s_add_i32 m0, s45, 0xc000
	ds_read_b128 v[188:191], v155
	ds_read_b128 v[196:199], v155 offset:1024
	ds_read_b128 v[200:203], v155 offset:2048
	ds_read_b128 v[204:207], v155 offset:3072
	ds_read_b128 v[208:211], v155 offset:4096
	ds_read_b128 v[212:215], v155 offset:5120
	ds_read_b128 v[216:219], v155 offset:6144
	ds_read_b128 v[220:223], v155 offset:7168
	global_load_lds_dwordx4 v[148:149], off
	v_lshl_add_u64 v[148:149], s[46:47], 0, v[138:139]
	s_add_i32 m0, s45, 0xe000
	s_nop 0
	global_load_lds_dwordx4 v[148:149], off
	s_waitcnt vmcnt(8)
	s_waitcnt lgkmcnt(0)
	s_barrier
	s_setprio 1
	s_waitcnt lgkmcnt(0)
	v_mfma_f32_16x16x32_bf16 v[124:127], v[144:147], v[188:191], 0
	v_mfma_f32_16x16x32_bf16 v[120:123], v[160:163], v[188:191], 0
	v_mfma_f32_16x16x32_bf16 v[112:115], v[144:147], v[200:203], 0
	v_mfma_f32_16x16x32_bf16 v[104:107], v[160:163], v[200:203], 0
	v_mfma_f32_16x16x32_bf16 v[96:99], v[144:147], v[208:211], 0
	v_mfma_f32_16x16x32_bf16 v[88:91], v[160:163], v[208:211], 0
	v_mfma_f32_16x16x32_bf16 v[80:83], v[144:147], v[216:219], 0
	v_mfma_f32_16x16x32_bf16 v[72:75], v[160:163], v[216:219], 0
	v_mfma_f32_16x16x32_bf16 v[124:127], v[156:159], v[196:199], v[124:127]
	v_mfma_f32_16x16x32_bf16 v[120:123], v[164:167], v[196:199], v[120:123]
	v_mfma_f32_16x16x32_bf16 v[112:115], v[156:159], v[204:207], v[112:115]
	v_mfma_f32_16x16x32_bf16 v[104:107], v[164:167], v[204:207], v[104:107]
	v_mfma_f32_16x16x32_bf16 v[96:99], v[156:159], v[212:215], v[96:99]
	v_mfma_f32_16x16x32_bf16 v[88:91], v[164:167], v[212:215], v[88:91]
	v_mfma_f32_16x16x32_bf16 v[80:83], v[156:159], v[220:223], v[80:83]
	v_mfma_f32_16x16x32_bf16 v[72:75], v[164:167], v[220:223], v[72:75]
	s_setprio 0
	s_setprio 1
	v_mfma_f32_16x16x32_bf16 v[116:119], v[168:171], v[188:191], 0
	v_mfma_f32_16x16x32_bf16 v[108:111], v[176:179], v[188:191], 0
	v_mfma_f32_16x16x32_bf16 v[100:103], v[168:171], v[200:203], 0
	v_mfma_f32_16x16x32_bf16 v[92:95], v[176:179], v[200:203], 0
	v_mfma_f32_16x16x32_bf16 v[84:87], v[168:171], v[208:211], 0
	v_mfma_f32_16x16x32_bf16 v[76:79], v[176:179], v[208:211], 0
	v_mfma_f32_16x16x32_bf16 v[68:71], v[168:171], v[216:219], 0
	v_mfma_f32_16x16x32_bf16 v[64:67], v[176:179], v[216:219], 0
	v_mfma_f32_16x16x32_bf16 v[116:119], v[172:175], v[196:199], v[116:119]
	v_mfma_f32_16x16x32_bf16 v[108:111], v[184:187], v[196:199], v[108:111]
	v_mfma_f32_16x16x32_bf16 v[100:103], v[172:175], v[204:207], v[100:103]
	v_mfma_f32_16x16x32_bf16 v[92:95], v[184:187], v[204:207], v[92:95]
	v_mfma_f32_16x16x32_bf16 v[84:87], v[172:175], v[212:215], v[84:87]
	v_mfma_f32_16x16x32_bf16 v[76:79], v[184:187], v[212:215], v[76:79]
	v_mfma_f32_16x16x32_bf16 v[68:71], v[172:175], v[220:223], v[68:71]
	v_mfma_f32_16x16x32_bf16 v[64:67], v[184:187], v[220:223], v[64:67]
	s_setprio 0
	s_barrier
	s_add_i32 s71, s63, s52
	v_lshl_add_u64 v[148:149], s[48:49], 0, v[132:133]
	s_mov_b32 m0, s71
	ds_read_b128 v[188:191], v155 offset:16384
	ds_read_b128 v[196:199], v155 offset:17408
	ds_read_b128 v[200:203], v155 offset:18432
	ds_read_b128 v[204:207], v155 offset:19456
	ds_read_b128 v[208:211], v155 offset:20480
	ds_read_b128 v[212:215], v155 offset:21504
	ds_read_b128 v[216:219], v155 offset:22528
	ds_read_b128 v[220:223], v155 offset:23552
	global_load_lds_dwordx4 v[148:149], off
	s_add_i32 m0, s71, 0x2000
	s_add_u32 s72, s48, 0x40000
	v_lshl_add_u64 v[180:181], s[48:49], 0, v[128:129]
	s_addc_u32 s73, s49, 0
	s_add_i32 s71, s64, s52
	global_load_lds_dwordx4 v[180:181], off
	v_lshl_add_u64 v[192:193], s[72:73], 0, v[132:133]
	s_mov_b32 m0, s71
	v_lshl_add_u64 v[224:225], s[50:51], 0, v[130:131]
	global_load_lds_dwordx4 v[192:193], off
	v_lshl_add_u64 v[192:193], s[72:73], 0, v[128:129]
	s_add_i32 m0, s71, 0x2000
	s_nop 0
	global_load_lds_dwordx4 v[192:193], off
	v_lshl_add_u64 v[192:193], s[50:51], 0, v[134:135]
	s_mov_b32 m0, s45
	s_nop 0
	global_load_lds_dwordx4 v[192:193], off
	s_mov_b32 m0, s55
	s_nop 0
	global_load_lds_dwordx4 v[224:225], off
	s_waitcnt vmcnt(8)
	s_waitcnt lgkmcnt(0)
	s_barrier
	s_setprio 1
	s_waitcnt lgkmcnt(0)
	v_mfma_f32_16x16x32_bf16 v[60:63], v[144:147], v[188:191], 0
	v_mfma_f32_16x16x32_bf16 v[56:59], v[160:163], v[188:191], 0
	v_mfma_f32_16x16x32_bf16 v[48:51], v[144:147], v[200:203], 0
	v_mfma_f32_16x16x32_bf16 v[40:43], v[160:163], v[200:203], 0
	v_mfma_f32_16x16x32_bf16 v[32:35], v[144:147], v[208:211], 0
	v_mfma_f32_16x16x32_bf16 v[24:27], v[160:163], v[208:211], 0
	v_mfma_f32_16x16x32_bf16 v[16:19], v[144:147], v[216:219], 0
	v_mfma_f32_16x16x32_bf16 v[8:11], v[160:163], v[216:219], 0
	v_mfma_f32_16x16x32_bf16 v[60:63], v[156:159], v[196:199], v[60:63]
	v_mfma_f32_16x16x32_bf16 v[56:59], v[164:167], v[196:199], v[56:59]
	v_mfma_f32_16x16x32_bf16 v[48:51], v[156:159], v[204:207], v[48:51]
	v_mfma_f32_16x16x32_bf16 v[40:43], v[164:167], v[204:207], v[40:43]
	v_mfma_f32_16x16x32_bf16 v[32:35], v[156:159], v[212:215], v[32:35]
	v_mfma_f32_16x16x32_bf16 v[24:27], v[164:167], v[212:215], v[24:27]
	v_mfma_f32_16x16x32_bf16 v[16:19], v[156:159], v[220:223], v[16:19]
	v_mfma_f32_16x16x32_bf16 v[8:11], v[164:167], v[220:223], v[8:11]
	s_setprio 0
	s_setprio 1
	v_mfma_f32_16x16x32_bf16 v[52:55], v[168:171], v[188:191], 0
	v_mfma_f32_16x16x32_bf16 v[44:47], v[176:179], v[188:191], 0
	v_mfma_f32_16x16x32_bf16 v[36:39], v[168:171], v[200:203], 0
	v_mfma_f32_16x16x32_bf16 v[28:31], v[176:179], v[200:203], 0
	v_mfma_f32_16x16x32_bf16 v[20:23], v[168:171], v[208:211], 0
	v_mfma_f32_16x16x32_bf16 v[12:15], v[176:179], v[208:211], 0
	v_mfma_f32_16x16x32_bf16 v[4:7], v[168:171], v[216:219], 0
	v_mfma_f32_16x16x32_bf16 v[0:3], v[176:179], v[216:219], 0
	v_mfma_f32_16x16x32_bf16 v[52:55], v[172:175], v[196:199], v[52:55]
	v_mfma_f32_16x16x32_bf16 v[44:47], v[184:187], v[196:199], v[44:47]
	v_mfma_f32_16x16x32_bf16 v[36:39], v[172:175], v[204:207], v[36:39]
	v_mfma_f32_16x16x32_bf16 v[28:31], v[184:187], v[204:207], v[28:31]
	v_mfma_f32_16x16x32_bf16 v[20:23], v[172:175], v[212:215], v[20:23]
	v_mfma_f32_16x16x32_bf16 v[12:15], v[184:187], v[212:215], v[12:15]
	v_mfma_f32_16x16x32_bf16 v[4:7], v[172:175], v[220:223], v[4:7]
	v_mfma_f32_16x16x32_bf16 v[0:3], v[184:187], v[220:223], v[0:3]
	s_setprio 0
	s_barrier
	s_add_i32 s71, 0, 0x18000
	s_add_i32 s72, 0, 0x1c000
	v_add_u32_e32 v164, s71, v151
	v_add_u32_e32 v183, s72, v151
	ds_read_b128 v[144:147], v164
	ds_read_b128 v[156:159], v164 offset:1024
	ds_read_b128 v[160:163], v164 offset:2048
	ds_read_b128 v[164:167], v164 offset:3072
	ds_read_b128 v[168:171], v183
	ds_read_b128 v[172:175], v183 offset:1024
	ds_read_b128 v[176:179], v183 offset:2048
	ds_read_b128 v[184:187], v183 offset:3072
	s_add_u32 s50, s50, 0x40000
	s_addc_u32 s51, s51, 0
	s_mov_b32 m0, s56
	v_lshl_add_u64 v[226:227], s[50:51], 0, v[134:135]
	ds_read_b128 v[188:191], v155 offset:32768
	ds_read_b128 v[196:199], v155 offset:33792
	ds_read_b128 v[200:203], v155 offset:34816
	ds_read_b128 v[204:207], v155 offset:35840
	ds_read_b128 v[208:211], v155 offset:36864
	ds_read_b128 v[212:215], v155 offset:37888
	ds_read_b128 v[216:219], v155 offset:38912
	ds_read_b128 v[220:223], v155 offset:39936
	global_load_lds_dwordx4 v[226:227], off
	v_lshl_add_u64 v[226:227], s[50:51], 0, v[130:131]
	s_mov_b32 m0, s57
	s_nop 0
	global_load_lds_dwordx4 v[226:227], off
	s_waitcnt vmcnt(8)
	s_waitcnt lgkmcnt(0)
	s_barrier
	s_setprio 1
	s_waitcnt lgkmcnt(0)
	v_mfma_f32_16x16x32_bf16 v[124:127], v[144:147], v[188:191], v[124:127]
	v_mfma_f32_16x16x32_bf16 v[120:123], v[160:163], v[188:191], v[120:123]
	v_mfma_f32_16x16x32_bf16 v[112:115], v[144:147], v[200:203], v[112:115]
	v_mfma_f32_16x16x32_bf16 v[104:107], v[160:163], v[200:203], v[104:107]
	v_mfma_f32_16x16x32_bf16 v[96:99], v[144:147], v[208:211], v[96:99]
	v_mfma_f32_16x16x32_bf16 v[88:91], v[160:163], v[208:211], v[88:91]
	v_mfma_f32_16x16x32_bf16 v[80:83], v[144:147], v[216:219], v[80:83]
	v_mfma_f32_16x16x32_bf16 v[72:75], v[160:163], v[216:219], v[72:75]
	v_mfma_f32_16x16x32_bf16 v[124:127], v[156:159], v[196:199], v[124:127]
	v_mfma_f32_16x16x32_bf16 v[120:123], v[164:167], v[196:199], v[120:123]
	v_mfma_f32_16x16x32_bf16 v[112:115], v[156:159], v[204:207], v[112:115]
	v_mfma_f32_16x16x32_bf16 v[104:107], v[164:167], v[204:207], v[104:107]
	v_mfma_f32_16x16x32_bf16 v[96:99], v[156:159], v[212:215], v[96:99]
	v_mfma_f32_16x16x32_bf16 v[88:91], v[164:167], v[212:215], v[88:91]
	v_mfma_f32_16x16x32_bf16 v[80:83], v[156:159], v[220:223], v[80:83]
	v_mfma_f32_16x16x32_bf16 v[72:75], v[164:167], v[220:223], v[72:75]
	s_setprio 0
	s_setprio 1
	v_mfma_f32_16x16x32_bf16 v[116:119], v[168:171], v[188:191], v[116:119]
	v_mfma_f32_16x16x32_bf16 v[108:111], v[176:179], v[188:191], v[108:111]
	v_mfma_f32_16x16x32_bf16 v[100:103], v[168:171], v[200:203], v[100:103]
	v_mfma_f32_16x16x32_bf16 v[92:95], v[176:179], v[200:203], v[92:95]
	v_mfma_f32_16x16x32_bf16 v[84:87], v[168:171], v[208:211], v[84:87]
	v_mfma_f32_16x16x32_bf16 v[76:79], v[176:179], v[208:211], v[76:79]
	v_mfma_f32_16x16x32_bf16 v[68:71], v[168:171], v[216:219], v[68:71]
	v_mfma_f32_16x16x32_bf16 v[64:67], v[176:179], v[216:219], v[64:67]
	v_mfma_f32_16x16x32_bf16 v[116:119], v[172:175], v[196:199], v[116:119]
	v_mfma_f32_16x16x32_bf16 v[108:111], v[184:187], v[196:199], v[108:111]
	v_mfma_f32_16x16x32_bf16 v[100:103], v[172:175], v[204:207], v[100:103]
	v_mfma_f32_16x16x32_bf16 v[92:95], v[184:187], v[204:207], v[92:95]
	v_mfma_f32_16x16x32_bf16 v[84:87], v[172:175], v[212:215], v[84:87]
	v_mfma_f32_16x16x32_bf16 v[76:79], v[184:187], v[212:215], v[76:79]
	v_mfma_f32_16x16x32_bf16 v[68:71], v[172:175], v[220:223], v[68:71]
	v_mfma_f32_16x16x32_bf16 v[64:67], v[184:187], v[220:223], v[64:67]
	s_setprio 0
	s_barrier
	s_add_i32 s50, s71, s52
	v_lshl_add_u64 v[148:149], v[148:149], 0, s[16:17]
	s_mov_b32 m0, s50
	ds_read_b128 v[188:191], v155 offset:49152
	ds_read_b128 v[196:199], v155 offset:50176
	ds_read_b128 v[200:203], v155 offset:51200
	ds_read_b128 v[204:207], v155 offset:52224
	ds_read_b128 v[208:211], v155 offset:53248
	ds_read_b128 v[212:215], v155 offset:54272
	ds_read_b128 v[216:219], v155 offset:55296
	ds_read_b128 v[220:223], v155 offset:56320
	global_load_lds_dwordx4 v[148:149], off
	s_add_i32 m0, s50, 0x2000
	s_add_u32 s48, s48, 0x40080
	v_lshl_add_u64 v[148:149], v[180:181], 0, s[16:17]
	s_addc_u32 s49, s49, 0
	s_add_i32 s50, s72, s52
	global_load_lds_dwordx4 v[148:149], off
	v_lshl_add_u64 v[148:149], s[48:49], 0, v[132:133]
	s_mov_b32 m0, s50
	s_nop 0
	global_load_lds_dwordx4 v[148:149], off
	v_lshl_add_u64 v[148:149], s[48:49], 0, v[128:129]
	s_add_i32 m0, s50, 0x2000
	s_nop 0
	global_load_lds_dwordx4 v[148:149], off
	v_lshl_add_u64 v[148:149], v[192:193], 0, s[16:17]
	s_mov_b32 m0, s59
	s_nop 0
	global_load_lds_dwordx4 v[148:149], off
	v_lshl_add_u64 v[148:149], v[224:225], 0, s[16:17]
	s_mov_b32 m0, s60
	s_nop 0
	global_load_lds_dwordx4 v[148:149], off
	s_waitcnt vmcnt(8)
	s_waitcnt lgkmcnt(0)
	s_barrier
	s_setprio 1
	s_waitcnt lgkmcnt(0)
	v_mfma_f32_16x16x32_bf16 v[60:63], v[144:147], v[188:191], v[60:63]
	v_mfma_f32_16x16x32_bf16 v[56:59], v[160:163], v[188:191], v[56:59]
	v_mfma_f32_16x16x32_bf16 v[48:51], v[144:147], v[200:203], v[48:51]
	v_mfma_f32_16x16x32_bf16 v[40:43], v[160:163], v[200:203], v[40:43]
	v_mfma_f32_16x16x32_bf16 v[32:35], v[144:147], v[208:211], v[32:35]
	v_mfma_f32_16x16x32_bf16 v[24:27], v[160:163], v[208:211], v[24:27]
	v_mfma_f32_16x16x32_bf16 v[16:19], v[144:147], v[216:219], v[16:19]
	v_mfma_f32_16x16x32_bf16 v[8:11], v[160:163], v[216:219], v[8:11]
	v_mfma_f32_16x16x32_bf16 v[60:63], v[156:159], v[196:199], v[60:63]
	v_mfma_f32_16x16x32_bf16 v[56:59], v[164:167], v[196:199], v[56:59]
	v_mfma_f32_16x16x32_bf16 v[48:51], v[156:159], v[204:207], v[48:51]
	v_mfma_f32_16x16x32_bf16 v[40:43], v[164:167], v[204:207], v[40:43]
	v_mfma_f32_16x16x32_bf16 v[32:35], v[156:159], v[212:215], v[32:35]
	v_mfma_f32_16x16x32_bf16 v[24:27], v[164:167], v[212:215], v[24:27]
	v_mfma_f32_16x16x32_bf16 v[16:19], v[156:159], v[220:223], v[16:19]
	v_mfma_f32_16x16x32_bf16 v[8:11], v[164:167], v[220:223], v[8:11]
	s_setprio 0
	s_setprio 1
	v_mfma_f32_16x16x32_bf16 v[52:55], v[168:171], v[188:191], v[52:55]
	v_mfma_f32_16x16x32_bf16 v[44:47], v[176:179], v[188:191], v[44:47]
	v_mfma_f32_16x16x32_bf16 v[36:39], v[168:171], v[200:203], v[36:39]
	v_mfma_f32_16x16x32_bf16 v[28:31], v[176:179], v[200:203], v[28:31]
	v_mfma_f32_16x16x32_bf16 v[20:23], v[168:171], v[208:211], v[20:23]
	v_mfma_f32_16x16x32_bf16 v[12:15], v[176:179], v[208:211], v[12:15]
	v_mfma_f32_16x16x32_bf16 v[4:7], v[168:171], v[216:219], v[4:7]
	v_mfma_f32_16x16x32_bf16 v[0:3], v[176:179], v[216:219], v[0:3]
	v_mfma_f32_16x16x32_bf16 v[52:55], v[172:175], v[196:199], v[52:55]
	v_mfma_f32_16x16x32_bf16 v[44:47], v[184:187], v[196:199], v[44:47]
	v_mfma_f32_16x16x32_bf16 v[36:39], v[172:175], v[204:207], v[36:39]
	v_mfma_f32_16x16x32_bf16 v[28:31], v[184:187], v[204:207], v[28:31]
	v_mfma_f32_16x16x32_bf16 v[20:23], v[172:175], v[212:215], v[20:23]
	v_mfma_f32_16x16x32_bf16 v[12:15], v[184:187], v[212:215], v[12:15]
	v_mfma_f32_16x16x32_bf16 v[4:7], v[172:175], v[220:223], v[4:7]
	v_mfma_f32_16x16x32_bf16 v[0:3], v[184:187], v[220:223], v[0:3]
	s_setprio 0
	s_barrier
	s_add_i32 s70, s70, 2
	s_add_u32 s46, s46, 0x100
	s_addc_u32 s47, s47, 0
	s_add_u32 s68, s68, 0x100
	s_addc_u32 s69, s69, 0
	s_cmp_gt_u32 s70, 13
	s_cbranch_scc0 .LBB0_1359
	s_branch .Lkpeel_done_1359

.Lkpeel_done_1359:
	s_and_b64 vcc, exec, s[18:19]
	s_cbranch_vccz .LBB0_1362
	s_barrier

.LBB0_1374:
	s_ashr_i32 s23, s22, 31
	s_lshl_b64 s[24:25], s[22:23], 19
	s_add_u32 s24, s3, s24
	s_addc_u32 s25, s31, s25
	s_and_b64 s[26:27], s[6:7], exec
	s_cselect_b32 s23, s25, s39
	s_cselect_b32 s60, s24, s38
	s_ashr_i32 s21, s20, 31
	s_lshl_b64 s[26:27], s[20:21], 19
	s_add_u32 s26, s40, s26
	s_addc_u32 s27, s41, s27
	s_and_b64 s[44:45], s[6:7], exec
	s_cselect_b32 s21, s27, s43
	s_cselect_b32 s61, s26, s42
	s_add_u32 s38, s38, 0x40080
	s_addc_u32 s39, s39, 0
	s_add_u32 s62, s42, 0x100
	s_addc_u32 s63, s43, 0
	s_mov_b32 s64, -2
	ds_read_b128 v[128:131], v181
	ds_read_b128 v[132:135], v181 offset:1024
	ds_read_b128 v[136:139], v181 offset:2048
	ds_read_b128 v[140:143], v181 offset:3072
	ds_read_b128 v[144:147], v183
	ds_read_b128 v[148:151], v183 offset:1024
	ds_read_b128 v[168:171], v183 offset:2048
	ds_read_b128 v[172:175], v183 offset:3072
	s_add_u32 s42, s38, 0xfffc0080
	s_addc_u32 s43, s39, -1
	s_cmp_eq_u32 s64, 12
	s_cselect_b32 s45, s23, s43
	s_cselect_b32 s44, s60, s42
	s_cselect_b32 s43, s21, s63
	s_cselect_b32 s42, s61, s62
	v_lshl_add_u64 v[176:177], s[38:39], 0, v[160:161]
	s_add_i32 m0, s37, 0xc000
	ds_read_b128 v[186:189], v184
	ds_read_b128 v[190:193], v184 offset:1024
	ds_read_b128 v[196:199], v184 offset:2048
	ds_read_b128 v[200:203], v184 offset:3072
	ds_read_b128 v[204:207], v184 offset:4096
	ds_read_b128 v[208:211], v184 offset:5120
	ds_read_b128 v[212:215], v184 offset:6144
	ds_read_b128 v[216:219], v184 offset:7168
	global_load_lds_dwordx4 v[176:177], off
	v_lshl_add_u64 v[176:177], s[38:39], 0, v[162:163]
	s_add_i32 m0, s37, 0xe000
	s_nop 0
	global_load_lds_dwordx4 v[176:177], off
	s_waitcnt vmcnt(8)
	s_waitcnt lgkmcnt(0)
	s_barrier
	s_setprio 1
	s_waitcnt lgkmcnt(0)
	v_mfma_f32_16x16x32_bf16 v[124:127], v[128:131], v[186:189], 0
	v_mfma_f32_16x16x32_bf16 v[120:123], v[136:139], v[186:189], 0
	v_mfma_f32_16x16x32_bf16 v[108:111], v[128:131], v[196:199], 0
	v_mfma_f32_16x16x32_bf16 v[104:107], v[136:139], v[196:199], 0
	v_mfma_f32_16x16x32_bf16 v[92:95], v[128:131], v[204:207], 0
	v_mfma_f32_16x16x32_bf16 v[88:91], v[136:139], v[204:207], 0
	v_mfma_f32_16x16x32_bf16 v[76:79], v[128:131], v[212:215], 0
	v_mfma_f32_16x16x32_bf16 v[72:75], v[136:139], v[212:215], 0
	v_mfma_f32_16x16x32_bf16 v[124:127], v[132:135], v[190:193], v[124:127]
	v_mfma_f32_16x16x32_bf16 v[120:123], v[140:143], v[190:193], v[120:123]
	v_mfma_f32_16x16x32_bf16 v[108:111], v[132:135], v[200:203], v[108:111]
	v_mfma_f32_16x16x32_bf16 v[104:107], v[140:143], v[200:203], v[104:107]
	v_mfma_f32_16x16x32_bf16 v[92:95], v[132:135], v[208:211], v[92:95]
	v_mfma_f32_16x16x32_bf16 v[88:91], v[140:143], v[208:211], v[88:91]
	v_mfma_f32_16x16x32_bf16 v[76:79], v[132:135], v[216:219], v[76:79]
	v_mfma_f32_16x16x32_bf16 v[72:75], v[140:143], v[216:219], v[72:75]
	s_setprio 0
	s_setprio 1
	v_mfma_f32_16x16x32_bf16 v[116:119], v[144:147], v[186:189], 0
	v_mfma_f32_16x16x32_bf16 v[112:115], v[168:171], v[186:189], 0
	v_mfma_f32_16x16x32_bf16 v[100:103], v[144:147], v[196:199], 0
	v_mfma_f32_16x16x32_bf16 v[96:99], v[168:171], v[196:199], 0
	v_mfma_f32_16x16x32_bf16 v[84:87], v[144:147], v[204:207], 0
	v_mfma_f32_16x16x32_bf16 v[80:83], v[168:171], v[204:207], 0
	v_mfma_f32_16x16x32_bf16 v[68:71], v[144:147], v[212:215], 0
	v_mfma_f32_16x16x32_bf16 v[64:67], v[168:171], v[212:215], 0
	v_mfma_f32_16x16x32_bf16 v[116:119], v[148:151], v[190:193], v[116:119]
	v_mfma_f32_16x16x32_bf16 v[112:115], v[172:175], v[190:193], v[112:115]
	v_mfma_f32_16x16x32_bf16 v[100:103], v[148:151], v[200:203], v[100:103]
	v_mfma_f32_16x16x32_bf16 v[96:99], v[172:175], v[200:203], v[96:99]
	v_mfma_f32_16x16x32_bf16 v[84:87], v[148:151], v[208:211], v[84:87]
	v_mfma_f32_16x16x32_bf16 v[80:83], v[172:175], v[208:211], v[80:83]
	v_mfma_f32_16x16x32_bf16 v[68:71], v[148:151], v[216:219], v[68:71]
	v_mfma_f32_16x16x32_bf16 v[64:67], v[172:175], v[216:219], v[64:67]
	s_setprio 0
	s_barrier
	s_add_i32 s65, s57, s46
	v_lshl_add_u64 v[176:177], s[42:43], 0, v[156:157]
	s_mov_b32 m0, s65
	ds_read_b128 v[186:189], v184 offset:16384
	ds_read_b128 v[190:193], v184 offset:17408
	ds_read_b128 v[196:199], v184 offset:18432
	ds_read_b128 v[200:203], v184 offset:19456
	ds_read_b128 v[204:207], v184 offset:20480
	ds_read_b128 v[208:211], v184 offset:21504
	ds_read_b128 v[212:215], v184 offset:22528
	ds_read_b128 v[216:219], v184 offset:23552
	global_load_lds_dwordx4 v[176:177], off
	s_add_i32 m0, s65, 0x2000
	s_add_u32 s66, s42, 0x40000
	v_lshl_add_u64 v[220:221], s[42:43], 0, v[152:153]
	s_addc_u32 s67, s43, 0
	s_add_i32 s65, s58, s46
	global_load_lds_dwordx4 v[220:221], off
	v_lshl_add_u64 v[222:223], s[66:67], 0, v[156:157]
	s_mov_b32 m0, s65
	v_lshl_add_u64 v[224:225], s[44:45], 0, v[154:155]
	global_load_lds_dwordx4 v[222:223], off
	v_lshl_add_u64 v[222:223], s[66:67], 0, v[152:153]
	s_add_i32 m0, s65, 0x2000
	s_nop 0
	global_load_lds_dwordx4 v[222:223], off
	v_lshl_add_u64 v[222:223], s[44:45], 0, v[158:159]
	s_mov_b32 m0, s37
	s_nop 0
	global_load_lds_dwordx4 v[222:223], off
	s_mov_b32 m0, s49
	s_nop 0
	global_load_lds_dwordx4 v[224:225], off
	s_waitcnt vmcnt(8)
	s_waitcnt lgkmcnt(0)
	s_barrier
	s_setprio 1
	s_waitcnt lgkmcnt(0)
	v_mfma_f32_16x16x32_bf16 v[60:63], v[128:131], v[186:189], 0
	v_mfma_f32_16x16x32_bf16 v[56:59], v[136:139], v[186:189], 0
	v_mfma_f32_16x16x32_bf16 v[44:47], v[128:131], v[196:199], 0
	v_mfma_f32_16x16x32_bf16 v[40:43], v[136:139], v[196:199], 0
	v_mfma_f32_16x16x32_bf16 v[28:31], v[128:131], v[204:207], 0
	v_mfma_f32_16x16x32_bf16 v[24:27], v[136:139], v[204:207], 0
	v_mfma_f32_16x16x32_bf16 v[12:15], v[128:131], v[212:215], 0
	v_mfma_f32_16x16x32_bf16 v[8:11], v[136:139], v[212:215], 0
	v_mfma_f32_16x16x32_bf16 v[60:63], v[132:135], v[190:193], v[60:63]
	v_mfma_f32_16x16x32_bf16 v[56:59], v[140:143], v[190:193], v[56:59]
	v_mfma_f32_16x16x32_bf16 v[44:47], v[132:135], v[200:203], v[44:47]
	v_mfma_f32_16x16x32_bf16 v[40:43], v[140:143], v[200:203], v[40:43]
	v_mfma_f32_16x16x32_bf16 v[28:31], v[132:135], v[208:211], v[28:31]
	v_mfma_f32_16x16x32_bf16 v[24:27], v[140:143], v[208:211], v[24:27]
	v_mfma_f32_16x16x32_bf16 v[12:15], v[132:135], v[216:219], v[12:15]
	v_mfma_f32_16x16x32_bf16 v[8:11], v[140:143], v[216:219], v[8:11]
	s_setprio 0
	s_setprio 1
	v_mfma_f32_16x16x32_bf16 v[52:55], v[144:147], v[186:189], 0
	v_mfma_f32_16x16x32_bf16 v[48:51], v[168:171], v[186:189], 0
	v_mfma_f32_16x16x32_bf16 v[36:39], v[144:147], v[196:199], 0
	v_mfma_f32_16x16x32_bf16 v[32:35], v[168:171], v[196:199], 0
	v_mfma_f32_16x16x32_bf16 v[20:23], v[144:147], v[204:207], 0
	v_mfma_f32_16x16x32_bf16 v[16:19], v[168:171], v[204:207], 0
	v_mfma_f32_16x16x32_bf16 v[4:7], v[144:147], v[212:215], 0
	v_mfma_f32_16x16x32_bf16 v[0:3], v[168:171], v[212:215], 0
	v_mfma_f32_16x16x32_bf16 v[52:55], v[148:151], v[190:193], v[52:55]
	v_mfma_f32_16x16x32_bf16 v[48:51], v[172:175], v[190:193], v[48:51]
	v_mfma_f32_16x16x32_bf16 v[36:39], v[148:151], v[200:203], v[36:39]
	v_mfma_f32_16x16x32_bf16 v[32:35], v[172:175], v[200:203], v[32:35]
	v_mfma_f32_16x16x32_bf16 v[20:23], v[148:151], v[208:211], v[20:23]
	v_mfma_f32_16x16x32_bf16 v[16:19], v[172:175], v[208:211], v[16:19]
	v_mfma_f32_16x16x32_bf16 v[4:7], v[148:151], v[216:219], v[4:7]
	v_mfma_f32_16x16x32_bf16 v[0:3], v[172:175], v[216:219], v[0:3]
	s_setprio 0
	s_barrier
	s_add_i32 s65, 0, 0x18000
	s_add_i32 s66, 0, 0x1c000
	v_add_u32_e32 v140, s65, v179
	v_add_u32_e32 v172, s66, v179
	ds_read_b128 v[128:131], v140
	ds_read_b128 v[132:135], v140 offset:1024
	ds_read_b128 v[136:139], v140 offset:2048
	ds_read_b128 v[140:143], v140 offset:3072
	ds_read_b128 v[144:147], v172
	ds_read_b128 v[148:151], v172 offset:1024
	ds_read_b128 v[168:171], v172 offset:2048
	ds_read_b128 v[172:175], v172 offset:3072
	s_add_u32 s44, s44, 0x40000
	s_addc_u32 s45, s45, 0
	s_mov_b32 m0, s50
	v_lshl_add_u64 v[226:227], s[44:45], 0, v[158:159]
	ds_read_b128 v[186:189], v184 offset:32768
	ds_read_b128 v[190:193], v184 offset:33792
	ds_read_b128 v[196:199], v184 offset:34816
	ds_read_b128 v[200:203], v184 offset:35840
	ds_read_b128 v[204:207], v184 offset:36864
	ds_read_b128 v[208:211], v184 offset:37888
	ds_read_b128 v[212:215], v184 offset:38912
	ds_read_b128 v[216:219], v184 offset:39936
	global_load_lds_dwordx4 v[226:227], off
	v_lshl_add_u64 v[226:227], s[44:45], 0, v[154:155]
	s_mov_b32 m0, s51
	s_nop 0
	global_load_lds_dwordx4 v[226:227], off
	s_waitcnt vmcnt(8)
	s_waitcnt lgkmcnt(0)
	s_barrier
	s_setprio 1
	s_waitcnt lgkmcnt(0)
	v_mfma_f32_16x16x32_bf16 v[124:127], v[128:131], v[186:189], v[124:127]
	v_mfma_f32_16x16x32_bf16 v[120:123], v[136:139], v[186:189], v[120:123]
	v_mfma_f32_16x16x32_bf16 v[108:111], v[128:131], v[196:199], v[108:111]
	v_mfma_f32_16x16x32_bf16 v[104:107], v[136:139], v[196:199], v[104:107]
	v_mfma_f32_16x16x32_bf16 v[92:95], v[128:131], v[204:207], v[92:95]
	v_mfma_f32_16x16x32_bf16 v[88:91], v[136:139], v[204:207], v[88:91]
	v_mfma_f32_16x16x32_bf16 v[76:79], v[128:131], v[212:215], v[76:79]
	v_mfma_f32_16x16x32_bf16 v[72:75], v[136:139], v[212:215], v[72:75]
	v_mfma_f32_16x16x32_bf16 v[124:127], v[132:135], v[190:193], v[124:127]
	v_mfma_f32_16x16x32_bf16 v[120:123], v[140:143], v[190:193], v[120:123]
	v_mfma_f32_16x16x32_bf16 v[108:111], v[132:135], v[200:203], v[108:111]
	v_mfma_f32_16x16x32_bf16 v[104:107], v[140:143], v[200:203], v[104:107]
	v_mfma_f32_16x16x32_bf16 v[92:95], v[132:135], v[208:211], v[92:95]
	v_mfma_f32_16x16x32_bf16 v[88:91], v[140:143], v[208:211], v[88:91]
	v_mfma_f32_16x16x32_bf16 v[76:79], v[132:135], v[216:219], v[76:79]
	v_mfma_f32_16x16x32_bf16 v[72:75], v[140:143], v[216:219], v[72:75]
	s_setprio 0
	s_setprio 1
	v_mfma_f32_16x16x32_bf16 v[116:119], v[144:147], v[186:189], v[116:119]
	v_mfma_f32_16x16x32_bf16 v[112:115], v[168:171], v[186:189], v[112:115]
	v_mfma_f32_16x16x32_bf16 v[100:103], v[144:147], v[196:199], v[100:103]
	v_mfma_f32_16x16x32_bf16 v[96:99], v[168:171], v[196:199], v[96:99]
	v_mfma_f32_16x16x32_bf16 v[84:87], v[144:147], v[204:207], v[84:87]
	v_mfma_f32_16x16x32_bf16 v[80:83], v[168:171], v[204:207], v[80:83]
	v_mfma_f32_16x16x32_bf16 v[68:71], v[144:147], v[212:215], v[68:71]
	v_mfma_f32_16x16x32_bf16 v[64:67], v[168:171], v[212:215], v[64:67]
	v_mfma_f32_16x16x32_bf16 v[116:119], v[148:151], v[190:193], v[116:119]
	v_mfma_f32_16x16x32_bf16 v[112:115], v[172:175], v[190:193], v[112:115]
	v_mfma_f32_16x16x32_bf16 v[100:103], v[148:151], v[200:203], v[100:103]
	v_mfma_f32_16x16x32_bf16 v[96:99], v[172:175], v[200:203], v[96:99]
	v_mfma_f32_16x16x32_bf16 v[84:87], v[148:151], v[208:211], v[84:87]
	v_mfma_f32_16x16x32_bf16 v[80:83], v[172:175], v[208:211], v[80:83]
	v_mfma_f32_16x16x32_bf16 v[68:71], v[148:151], v[216:219], v[68:71]
	v_mfma_f32_16x16x32_bf16 v[64:67], v[172:175], v[216:219], v[64:67]
	s_setprio 0
	s_barrier
	s_add_i32 s44, s65, s46
	v_lshl_add_u64 v[176:177], v[176:177], 0, s[16:17]
	s_mov_b32 m0, s44
	ds_read_b128 v[186:189], v184 offset:49152
	ds_read_b128 v[190:193], v184 offset:50176
	ds_read_b128 v[196:199], v184 offset:51200
	ds_read_b128 v[200:203], v184 offset:52224
	ds_read_b128 v[204:207], v184 offset:53248
	ds_read_b128 v[208:211], v184 offset:54272
	ds_read_b128 v[212:215], v184 offset:55296
	ds_read_b128 v[216:219], v184 offset:56320
	global_load_lds_dwordx4 v[176:177], off
	s_add_i32 m0, s44, 0x2000
	s_add_u32 s42, s42, 0x40080
	v_lshl_add_u64 v[176:177], v[220:221], 0, s[16:17]
	s_addc_u32 s43, s43, 0
	s_add_i32 s44, s66, s46
	global_load_lds_dwordx4 v[176:177], off
	v_lshl_add_u64 v[176:177], s[42:43], 0, v[156:157]
	s_mov_b32 m0, s44
	s_nop 0
	global_load_lds_dwordx4 v[176:177], off
	v_lshl_add_u64 v[176:177], s[42:43], 0, v[152:153]
	s_add_i32 m0, s44, 0x2000
	s_nop 0
	global_load_lds_dwordx4 v[176:177], off
	v_lshl_add_u64 v[176:177], v[222:223], 0, s[16:17]
	s_mov_b32 m0, s53
	s_nop 0
	global_load_lds_dwordx4 v[176:177], off
	v_lshl_add_u64 v[176:177], v[224:225], 0, s[16:17]
	s_mov_b32 m0, s54
	s_nop 0
	global_load_lds_dwordx4 v[176:177], off
	s_waitcnt vmcnt(8)
	s_waitcnt lgkmcnt(0)
	s_barrier
	s_setprio 1
	s_waitcnt lgkmcnt(0)
	v_mfma_f32_16x16x32_bf16 v[60:63], v[128:131], v[186:189], v[60:63]
	v_mfma_f32_16x16x32_bf16 v[56:59], v[136:139], v[186:189], v[56:59]
	v_mfma_f32_16x16x32_bf16 v[44:47], v[128:131], v[196:199], v[44:47]
	v_mfma_f32_16x16x32_bf16 v[40:43], v[136:139], v[196:199], v[40:43]
	v_mfma_f32_16x16x32_bf16 v[28:31], v[128:131], v[204:207], v[28:31]
	v_mfma_f32_16x16x32_bf16 v[24:27], v[136:139], v[204:207], v[24:27]
	v_mfma_f32_16x16x32_bf16 v[12:15], v[128:131], v[212:215], v[12:15]
	v_mfma_f32_16x16x32_bf16 v[8:11], v[136:139], v[212:215], v[8:11]
	v_mfma_f32_16x16x32_bf16 v[60:63], v[132:135], v[190:193], v[60:63]
	v_mfma_f32_16x16x32_bf16 v[56:59], v[140:143], v[190:193], v[56:59]
	v_mfma_f32_16x16x32_bf16 v[44:47], v[132:135], v[200:203], v[44:47]
	v_mfma_f32_16x16x32_bf16 v[40:43], v[140:143], v[200:203], v[40:43]
	v_mfma_f32_16x16x32_bf16 v[28:31], v[132:135], v[208:211], v[28:31]
	v_mfma_f32_16x16x32_bf16 v[24:27], v[140:143], v[208:211], v[24:27]
	v_mfma_f32_16x16x32_bf16 v[12:15], v[132:135], v[216:219], v[12:15]
	v_mfma_f32_16x16x32_bf16 v[8:11], v[140:143], v[216:219], v[8:11]
	s_setprio 0
	s_setprio 1
	v_mfma_f32_16x16x32_bf16 v[52:55], v[144:147], v[186:189], v[52:55]
	v_mfma_f32_16x16x32_bf16 v[48:51], v[168:171], v[186:189], v[48:51]
	v_mfma_f32_16x16x32_bf16 v[36:39], v[144:147], v[196:199], v[36:39]
	v_mfma_f32_16x16x32_bf16 v[32:35], v[168:171], v[196:199], v[32:35]
	v_mfma_f32_16x16x32_bf16 v[20:23], v[144:147], v[204:207], v[20:23]
	v_mfma_f32_16x16x32_bf16 v[16:19], v[168:171], v[204:207], v[16:19]
	v_mfma_f32_16x16x32_bf16 v[4:7], v[144:147], v[212:215], v[4:7]
	v_mfma_f32_16x16x32_bf16 v[0:3], v[168:171], v[212:215], v[0:3]
	v_mfma_f32_16x16x32_bf16 v[52:55], v[148:151], v[190:193], v[52:55]
	v_mfma_f32_16x16x32_bf16 v[48:51], v[172:175], v[190:193], v[48:51]
	v_mfma_f32_16x16x32_bf16 v[36:39], v[148:151], v[200:203], v[36:39]
	v_mfma_f32_16x16x32_bf16 v[32:35], v[172:175], v[200:203], v[32:35]
	v_mfma_f32_16x16x32_bf16 v[20:23], v[148:151], v[208:211], v[20:23]
	v_mfma_f32_16x16x32_bf16 v[16:19], v[172:175], v[208:211], v[16:19]
	v_mfma_f32_16x16x32_bf16 v[4:7], v[148:151], v[216:219], v[4:7]
	v_mfma_f32_16x16x32_bf16 v[0:3], v[172:175], v[216:219], v[0:3]
	s_setprio 0
	s_barrier
	s_add_i32 s64, s64, 2
	s_add_u32 s38, s38, 0x100
	s_addc_u32 s39, s39, 0
	s_add_u32 s62, s62, 0x100
	s_addc_u32 s63, s63, 0
	s_cmp_gt_u32 s64, 13
	s_cbranch_scc0 .LBB0_1375
	s_branch .Lkpeel_done_1375

.LBB0_1442:
	s_ashr_i32 s43, s42, 31
	s_lshl_b64 s[44:45], s[42:43], 19
	s_add_u32 s44, s3, s44
	s_addc_u32 s45, s23, s45
	s_and_b64 s[46:47], s[6:7], exec
	s_cselect_b32 s43, s45, s51
	s_cselect_b32 s69, s44, s50
	s_ashr_i32 s39, s38, 31
	s_lshl_b64 s[46:47], s[38:39], 19
	s_add_u32 s46, s31, s46
	s_addc_u32 s47, s40, s47
	s_and_b64 s[54:55], s[6:7], exec
	s_cselect_b32 s39, s47, s53
	s_cselect_b32 s70, s46, s52
	s_add_u32 s50, s50, 0x40080
	s_addc_u32 s51, s51, 0
	s_add_u32 s71, s52, 0x100
	s_addc_u32 s72, s53, 0
	s_mov_b32 s73, -2
	ds_read_b128 v[144:147], v155
	ds_read_b128 v[148:151], v155 offset:1024
	ds_read_b128 v[158:161], v155 offset:2048
	ds_read_b128 v[162:165], v155 offset:3072
	ds_read_b128 v[166:169], v156
	ds_read_b128 v[170:173], v156 offset:1024
	ds_read_b128 v[174:177], v156 offset:2048
	ds_read_b128 v[178:181], v156 offset:3072
	s_add_u32 s52, s50, 0xfffc0080
	s_addc_u32 s53, s51, -1
	s_cmp_eq_u32 s73, 12
	s_cselect_b32 s55, s43, s53
	s_cselect_b32 s54, s69, s52
	s_cselect_b32 s53, s39, s72
	s_cselect_b32 s52, s70, s71
	v_lshl_add_u64 v[192:193], s[50:51], 0, v[136:137]
	s_add_i32 m0, s49, 0xc000
	ds_read_b128 v[184:187], v157
	ds_read_b128 v[188:191], v157 offset:1024
	ds_read_b128 v[196:199], v157 offset:2048
	ds_read_b128 v[200:203], v157 offset:3072
	ds_read_b128 v[204:207], v157 offset:4096
	ds_read_b128 v[208:211], v157 offset:5120
	ds_read_b128 v[212:215], v157 offset:6144
	ds_read_b128 v[216:219], v157 offset:7168
	global_load_lds_dwordx4 v[192:193], off
	v_lshl_add_u64 v[192:193], s[50:51], 0, v[138:139]
	s_add_i32 m0, s49, 0xe000
	s_nop 0
	global_load_lds_dwordx4 v[192:193], off
	s_waitcnt vmcnt(8)
	s_waitcnt lgkmcnt(0)
	s_barrier
	s_setprio 1
	s_waitcnt lgkmcnt(0)
	v_mfma_f32_16x16x32_bf16 v[124:127], v[144:147], v[184:187], 0
	v_mfma_f32_16x16x32_bf16 v[120:123], v[158:161], v[184:187], 0
	v_mfma_f32_16x16x32_bf16 v[116:119], v[144:147], v[196:199], 0
	v_mfma_f32_16x16x32_bf16 v[112:115], v[158:161], v[196:199], 0
	v_mfma_f32_16x16x32_bf16 v[96:99], v[144:147], v[204:207], 0
	v_mfma_f32_16x16x32_bf16 v[88:91], v[158:161], v[204:207], 0
	v_mfma_f32_16x16x32_bf16 v[80:83], v[144:147], v[212:215], 0
	v_mfma_f32_16x16x32_bf16 v[72:75], v[158:161], v[212:215], 0
	v_mfma_f32_16x16x32_bf16 v[124:127], v[148:151], v[188:191], v[124:127]
	v_mfma_f32_16x16x32_bf16 v[120:123], v[162:165], v[188:191], v[120:123]
	v_mfma_f32_16x16x32_bf16 v[116:119], v[148:151], v[200:203], v[116:119]
	v_mfma_f32_16x16x32_bf16 v[112:115], v[162:165], v[200:203], v[112:115]
	v_mfma_f32_16x16x32_bf16 v[96:99], v[148:151], v[208:211], v[96:99]
	v_mfma_f32_16x16x32_bf16 v[88:91], v[162:165], v[208:211], v[88:91]
	v_mfma_f32_16x16x32_bf16 v[80:83], v[148:151], v[216:219], v[80:83]
	v_mfma_f32_16x16x32_bf16 v[72:75], v[162:165], v[216:219], v[72:75]
	s_setprio 0
	s_setprio 1
	v_mfma_f32_16x16x32_bf16 v[108:111], v[166:169], v[184:187], 0
	v_mfma_f32_16x16x32_bf16 v[104:107], v[174:177], v[184:187], 0
	v_mfma_f32_16x16x32_bf16 v[100:103], v[166:169], v[196:199], 0
	v_mfma_f32_16x16x32_bf16 v[92:95], v[174:177], v[196:199], 0
	v_mfma_f32_16x16x32_bf16 v[84:87], v[166:169], v[204:207], 0
	v_mfma_f32_16x16x32_bf16 v[76:79], v[174:177], v[204:207], 0
	v_mfma_f32_16x16x32_bf16 v[68:71], v[166:169], v[212:215], 0
	v_mfma_f32_16x16x32_bf16 v[64:67], v[174:177], v[212:215], 0
	v_mfma_f32_16x16x32_bf16 v[108:111], v[170:173], v[188:191], v[108:111]
	v_mfma_f32_16x16x32_bf16 v[104:107], v[178:181], v[188:191], v[104:107]
	v_mfma_f32_16x16x32_bf16 v[100:103], v[170:173], v[200:203], v[100:103]
	v_mfma_f32_16x16x32_bf16 v[92:95], v[178:181], v[200:203], v[92:95]
	v_mfma_f32_16x16x32_bf16 v[84:87], v[170:173], v[208:211], v[84:87]
	v_mfma_f32_16x16x32_bf16 v[76:79], v[178:181], v[208:211], v[76:79]
	v_mfma_f32_16x16x32_bf16 v[68:71], v[170:173], v[216:219], v[68:71]
	v_mfma_f32_16x16x32_bf16 v[64:67], v[178:181], v[216:219], v[64:67]
	s_setprio 0
	s_barrier
	s_add_i32 s74, s66, s41
	v_lshl_add_u64 v[192:193], s[52:53], 0, v[132:133]
	s_mov_b32 m0, s74
	ds_read_b128 v[184:187], v157 offset:16384
	ds_read_b128 v[188:191], v157 offset:17408
	ds_read_b128 v[196:199], v157 offset:18432
	ds_read_b128 v[200:203], v157 offset:19456
	ds_read_b128 v[204:207], v157 offset:20480
	ds_read_b128 v[208:211], v157 offset:21504
	ds_read_b128 v[212:215], v157 offset:22528
	ds_read_b128 v[216:219], v157 offset:23552
	global_load_lds_dwordx4 v[192:193], off
	s_add_i32 m0, s74, 0x2000
	s_add_u32 s76, s52, 0x40000
	v_lshl_add_u64 v[220:221], s[52:53], 0, v[128:129]
	s_addc_u32 s77, s53, 0
	s_add_i32 s74, s67, s41
	global_load_lds_dwordx4 v[220:221], off
	v_lshl_add_u64 v[222:223], s[76:77], 0, v[132:133]
	s_mov_b32 m0, s74
	v_lshl_add_u64 v[224:225], s[54:55], 0, v[130:131]
	global_load_lds_dwordx4 v[222:223], off
	v_lshl_add_u64 v[222:223], s[76:77], 0, v[128:129]
	s_add_i32 m0, s74, 0x2000
	s_nop 0
	global_load_lds_dwordx4 v[222:223], off
	v_lshl_add_u64 v[222:223], s[54:55], 0, v[134:135]
	s_mov_b32 m0, s49
	s_nop 0
	global_load_lds_dwordx4 v[222:223], off
	s_mov_b32 m0, s58
	s_nop 0
	global_load_lds_dwordx4 v[224:225], off
	s_waitcnt vmcnt(8)
	s_waitcnt lgkmcnt(0)
	s_barrier
	s_setprio 1
	s_waitcnt lgkmcnt(0)
	v_mfma_f32_16x16x32_bf16 v[60:63], v[144:147], v[184:187], 0
	v_mfma_f32_16x16x32_bf16 v[56:59], v[158:161], v[184:187], 0
	v_mfma_f32_16x16x32_bf16 v[48:51], v[144:147], v[196:199], 0
	v_mfma_f32_16x16x32_bf16 v[40:43], v[158:161], v[196:199], 0
	v_mfma_f32_16x16x32_bf16 v[32:35], v[144:147], v[204:207], 0
	v_mfma_f32_16x16x32_bf16 v[24:27], v[158:161], v[204:207], 0
	v_mfma_f32_16x16x32_bf16 v[16:19], v[144:147], v[212:215], 0
	v_mfma_f32_16x16x32_bf16 v[8:11], v[158:161], v[212:215], 0
	v_mfma_f32_16x16x32_bf16 v[60:63], v[148:151], v[188:191], v[60:63]
	v_mfma_f32_16x16x32_bf16 v[56:59], v[162:165], v[188:191], v[56:59]
	v_mfma_f32_16x16x32_bf16 v[48:51], v[148:151], v[200:203], v[48:51]
	v_mfma_f32_16x16x32_bf16 v[40:43], v[162:165], v[200:203], v[40:43]
	v_mfma_f32_16x16x32_bf16 v[32:35], v[148:151], v[208:211], v[32:35]
	v_mfma_f32_16x16x32_bf16 v[24:27], v[162:165], v[208:211], v[24:27]
	v_mfma_f32_16x16x32_bf16 v[16:19], v[148:151], v[216:219], v[16:19]
	v_mfma_f32_16x16x32_bf16 v[8:11], v[162:165], v[216:219], v[8:11]
	s_setprio 0
	s_setprio 1
	v_mfma_f32_16x16x32_bf16 v[52:55], v[166:169], v[184:187], 0
	v_mfma_f32_16x16x32_bf16 v[44:47], v[174:177], v[184:187], 0
	v_mfma_f32_16x16x32_bf16 v[36:39], v[166:169], v[196:199], 0
	v_mfma_f32_16x16x32_bf16 v[28:31], v[174:177], v[196:199], 0
	v_mfma_f32_16x16x32_bf16 v[20:23], v[166:169], v[204:207], 0
	v_mfma_f32_16x16x32_bf16 v[12:15], v[174:177], v[204:207], 0
	v_mfma_f32_16x16x32_bf16 v[4:7], v[166:169], v[212:215], 0
	v_mfma_f32_16x16x32_bf16 v[0:3], v[174:177], v[212:215], 0
	v_mfma_f32_16x16x32_bf16 v[52:55], v[170:173], v[188:191], v[52:55]
	v_mfma_f32_16x16x32_bf16 v[44:47], v[178:181], v[188:191], v[44:47]
	v_mfma_f32_16x16x32_bf16 v[36:39], v[170:173], v[200:203], v[36:39]
	v_mfma_f32_16x16x32_bf16 v[28:31], v[178:181], v[200:203], v[28:31]
	v_mfma_f32_16x16x32_bf16 v[20:23], v[170:173], v[208:211], v[20:23]
	v_mfma_f32_16x16x32_bf16 v[12:15], v[178:181], v[208:211], v[12:15]
	v_mfma_f32_16x16x32_bf16 v[4:7], v[170:173], v[216:219], v[4:7]
	v_mfma_f32_16x16x32_bf16 v[0:3], v[178:181], v[216:219], v[0:3]
	s_setprio 0
	s_barrier
	s_add_i32 s74, 0, 0x18000
	s_add_i32 s76, 0, 0x1c000
	v_add_u32_e32 v162, s74, v153
	v_add_u32_e32 v178, s76, v153
	ds_read_b128 v[144:147], v162
	ds_read_b128 v[148:151], v162 offset:1024
	ds_read_b128 v[158:161], v162 offset:2048
	ds_read_b128 v[162:165], v162 offset:3072
	ds_read_b128 v[166:169], v178
	ds_read_b128 v[170:173], v178 offset:1024
	ds_read_b128 v[174:177], v178 offset:2048
	ds_read_b128 v[178:181], v178 offset:3072
	s_add_u32 s54, s54, 0x40000
	s_addc_u32 s55, s55, 0
	s_mov_b32 m0, s59
	v_lshl_add_u64 v[226:227], s[54:55], 0, v[134:135]
	ds_read_b128 v[184:187], v157 offset:32768
	ds_read_b128 v[188:191], v157 offset:33792
	ds_read_b128 v[196:199], v157 offset:34816
	ds_read_b128 v[200:203], v157 offset:35840
	ds_read_b128 v[204:207], v157 offset:36864
	ds_read_b128 v[208:211], v157 offset:37888
	ds_read_b128 v[212:215], v157 offset:38912
	ds_read_b128 v[216:219], v157 offset:39936
	global_load_lds_dwordx4 v[226:227], off
	v_lshl_add_u64 v[226:227], s[54:55], 0, v[130:131]
	s_mov_b32 m0, s60
	s_nop 0
	global_load_lds_dwordx4 v[226:227], off
	s_waitcnt vmcnt(8)
	s_waitcnt lgkmcnt(0)
	s_barrier
	s_setprio 1
	s_waitcnt lgkmcnt(0)
	v_mfma_f32_16x16x32_bf16 v[124:127], v[144:147], v[184:187], v[124:127]
	v_mfma_f32_16x16x32_bf16 v[120:123], v[158:161], v[184:187], v[120:123]
	v_mfma_f32_16x16x32_bf16 v[116:119], v[144:147], v[196:199], v[116:119]
	v_mfma_f32_16x16x32_bf16 v[112:115], v[158:161], v[196:199], v[112:115]
	v_mfma_f32_16x16x32_bf16 v[96:99], v[144:147], v[204:207], v[96:99]
	v_mfma_f32_16x16x32_bf16 v[88:91], v[158:161], v[204:207], v[88:91]
	v_mfma_f32_16x16x32_bf16 v[80:83], v[144:147], v[212:215], v[80:83]
	v_mfma_f32_16x16x32_bf16 v[72:75], v[158:161], v[212:215], v[72:75]
	v_mfma_f32_16x16x32_bf16 v[124:127], v[148:151], v[188:191], v[124:127]
	v_mfma_f32_16x16x32_bf16 v[120:123], v[162:165], v[188:191], v[120:123]
	v_mfma_f32_16x16x32_bf16 v[116:119], v[148:151], v[200:203], v[116:119]
	v_mfma_f32_16x16x32_bf16 v[112:115], v[162:165], v[200:203], v[112:115]
	v_mfma_f32_16x16x32_bf16 v[96:99], v[148:151], v[208:211], v[96:99]
	v_mfma_f32_16x16x32_bf16 v[88:91], v[162:165], v[208:211], v[88:91]
	v_mfma_f32_16x16x32_bf16 v[80:83], v[148:151], v[216:219], v[80:83]
	v_mfma_f32_16x16x32_bf16 v[72:75], v[162:165], v[216:219], v[72:75]
	s_setprio 0
	s_setprio 1
	v_mfma_f32_16x16x32_bf16 v[108:111], v[166:169], v[184:187], v[108:111]
	v_mfma_f32_16x16x32_bf16 v[104:107], v[174:177], v[184:187], v[104:107]
	v_mfma_f32_16x16x32_bf16 v[100:103], v[166:169], v[196:199], v[100:103]
	v_mfma_f32_16x16x32_bf16 v[92:95], v[174:177], v[196:199], v[92:95]
	v_mfma_f32_16x16x32_bf16 v[84:87], v[166:169], v[204:207], v[84:87]
	v_mfma_f32_16x16x32_bf16 v[76:79], v[174:177], v[204:207], v[76:79]
	v_mfma_f32_16x16x32_bf16 v[68:71], v[166:169], v[212:215], v[68:71]
	v_mfma_f32_16x16x32_bf16 v[64:67], v[174:177], v[212:215], v[64:67]
	v_mfma_f32_16x16x32_bf16 v[108:111], v[170:173], v[188:191], v[108:111]
	v_mfma_f32_16x16x32_bf16 v[104:107], v[178:181], v[188:191], v[104:107]
	v_mfma_f32_16x16x32_bf16 v[100:103], v[170:173], v[200:203], v[100:103]
	v_mfma_f32_16x16x32_bf16 v[92:95], v[178:181], v[200:203], v[92:95]
	v_mfma_f32_16x16x32_bf16 v[84:87], v[170:173], v[208:211], v[84:87]
	v_mfma_f32_16x16x32_bf16 v[76:79], v[178:181], v[208:211], v[76:79]
	v_mfma_f32_16x16x32_bf16 v[68:71], v[170:173], v[216:219], v[68:71]
	v_mfma_f32_16x16x32_bf16 v[64:67], v[178:181], v[216:219], v[64:67]
	s_setprio 0
	s_barrier
	s_add_i32 s54, s74, s41
	v_lshl_add_u64 v[192:193], v[192:193], 0, s[18:19]
	s_mov_b32 m0, s54
	ds_read_b128 v[184:187], v157 offset:49152
	ds_read_b128 v[188:191], v157 offset:50176
	ds_read_b128 v[196:199], v157 offset:51200
	ds_read_b128 v[200:203], v157 offset:52224
	ds_read_b128 v[204:207], v157 offset:53248
	ds_read_b128 v[208:211], v157 offset:54272
	ds_read_b128 v[212:215], v157 offset:55296
	ds_read_b128 v[216:219], v157 offset:56320
	global_load_lds_dwordx4 v[192:193], off
	s_add_i32 m0, s54, 0x2000
	s_add_u32 s52, s52, 0x40080
	v_lshl_add_u64 v[192:193], v[220:221], 0, s[18:19]
	s_addc_u32 s53, s53, 0
	s_add_i32 s54, s76, s41
	global_load_lds_dwordx4 v[192:193], off
	v_lshl_add_u64 v[192:193], s[52:53], 0, v[132:133]
	s_mov_b32 m0, s54
	s_nop 0
	global_load_lds_dwordx4 v[192:193], off
	v_lshl_add_u64 v[192:193], s[52:53], 0, v[128:129]
	s_add_i32 m0, s54, 0x2000
	s_nop 0
	global_load_lds_dwordx4 v[192:193], off
	v_lshl_add_u64 v[192:193], v[222:223], 0, s[18:19]
	s_mov_b32 m0, s62
	s_nop 0
	global_load_lds_dwordx4 v[192:193], off
	v_lshl_add_u64 v[192:193], v[224:225], 0, s[18:19]
	s_mov_b32 m0, s63
	s_nop 0
	global_load_lds_dwordx4 v[192:193], off
	s_waitcnt vmcnt(8)
	s_waitcnt lgkmcnt(0)
	s_barrier
	s_setprio 1
	s_waitcnt lgkmcnt(0)
	v_mfma_f32_16x16x32_bf16 v[60:63], v[144:147], v[184:187], v[60:63]
	v_mfma_f32_16x16x32_bf16 v[56:59], v[158:161], v[184:187], v[56:59]
	v_mfma_f32_16x16x32_bf16 v[48:51], v[144:147], v[196:199], v[48:51]
	v_mfma_f32_16x16x32_bf16 v[40:43], v[158:161], v[196:199], v[40:43]
	v_mfma_f32_16x16x32_bf16 v[32:35], v[144:147], v[204:207], v[32:35]
	v_mfma_f32_16x16x32_bf16 v[24:27], v[158:161], v[204:207], v[24:27]
	v_mfma_f32_16x16x32_bf16 v[16:19], v[144:147], v[212:215], v[16:19]
	v_mfma_f32_16x16x32_bf16 v[8:11], v[158:161], v[212:215], v[8:11]
	v_mfma_f32_16x16x32_bf16 v[60:63], v[148:151], v[188:191], v[60:63]
	v_mfma_f32_16x16x32_bf16 v[56:59], v[162:165], v[188:191], v[56:59]
	v_mfma_f32_16x16x32_bf16 v[48:51], v[148:151], v[200:203], v[48:51]
	v_mfma_f32_16x16x32_bf16 v[40:43], v[162:165], v[200:203], v[40:43]
	v_mfma_f32_16x16x32_bf16 v[32:35], v[148:151], v[208:211], v[32:35]
	v_mfma_f32_16x16x32_bf16 v[24:27], v[162:165], v[208:211], v[24:27]
	v_mfma_f32_16x16x32_bf16 v[16:19], v[148:151], v[216:219], v[16:19]
	v_mfma_f32_16x16x32_bf16 v[8:11], v[162:165], v[216:219], v[8:11]
	s_setprio 0
	s_setprio 1
	v_mfma_f32_16x16x32_bf16 v[52:55], v[166:169], v[184:187], v[52:55]
	v_mfma_f32_16x16x32_bf16 v[44:47], v[174:177], v[184:187], v[44:47]
	v_mfma_f32_16x16x32_bf16 v[36:39], v[166:169], v[196:199], v[36:39]
	v_mfma_f32_16x16x32_bf16 v[28:31], v[174:177], v[196:199], v[28:31]
	v_mfma_f32_16x16x32_bf16 v[20:23], v[166:169], v[204:207], v[20:23]
	v_mfma_f32_16x16x32_bf16 v[12:15], v[174:177], v[204:207], v[12:15]
	v_mfma_f32_16x16x32_bf16 v[4:7], v[166:169], v[212:215], v[4:7]
	v_mfma_f32_16x16x32_bf16 v[0:3], v[174:177], v[212:215], v[0:3]
	v_mfma_f32_16x16x32_bf16 v[52:55], v[170:173], v[188:191], v[52:55]
	v_mfma_f32_16x16x32_bf16 v[44:47], v[178:181], v[188:191], v[44:47]
	v_mfma_f32_16x16x32_bf16 v[36:39], v[170:173], v[200:203], v[36:39]
	v_mfma_f32_16x16x32_bf16 v[28:31], v[178:181], v[200:203], v[28:31]
	v_mfma_f32_16x16x32_bf16 v[20:23], v[170:173], v[208:211], v[20:23]
	v_mfma_f32_16x16x32_bf16 v[12:15], v[178:181], v[208:211], v[12:15]
	v_mfma_f32_16x16x32_bf16 v[4:7], v[170:173], v[216:219], v[4:7]
	v_mfma_f32_16x16x32_bf16 v[0:3], v[178:181], v[216:219], v[0:3]
	s_setprio 0
	s_barrier
	s_add_i32 s73, s73, 2
	s_add_u32 s50, s50, 0x100
	s_addc_u32 s51, s51, 0
	s_add_u32 s71, s71, 0x100
	s_addc_u32 s72, s72, 0
	s_cmp_gt_u32 s73, 13
	s_cbranch_scc0 .LBB0_1443
	s_branch .Lkpeel_done_1443

.Lkpeel_done_1443:
	s_and_b64 vcc, exec, s[20:21]
	s_cbranch_vccz .LBB0_1446
	s_barrier

.LBB0_1573:
	s_ashr_i32 s21, s20, 31
	s_lshl_b64 s[22:23], s[20:21], 19
	s_add_u32 s22, s31, s22
	s_addc_u32 s23, s42, s23
	s_and_b64 s[24:25], s[6:7], exec
	s_cselect_b32 s21, s23, s37
	s_cselect_b32 s58, s22, s36
	s_ashr_i32 s19, s18, 31
	s_lshl_b64 s[24:25], s[18:19], 19
	s_add_u32 s24, s43, s24
	s_addc_u32 s25, s44, s25
	s_and_b64 s[40:41], s[6:7], exec
	s_cselect_b32 s19, s25, s39
	s_cselect_b32 s59, s24, s38
	s_add_u32 s36, s36, 0x40080
	s_addc_u32 s37, s37, 0
	s_add_u32 s60, s38, 0x100
	s_addc_u32 s61, s39, 0
	s_mov_b32 s62, -2
	ds_read_b128 v[150:153], v147
	ds_read_b128 v[154:157], v147 offset:1024
	ds_read_b128 v[158:161], v147 offset:2048
	ds_read_b128 v[162:165], v147 offset:3072
	ds_read_b128 v[166:169], v148
	ds_read_b128 v[170:173], v148 offset:1024
	ds_read_b128 v[174:177], v148 offset:2048
	ds_read_b128 v[178:181], v148 offset:3072
	s_add_u32 s38, s36, 0xfffc0080
	s_addc_u32 s39, s37, -1
	s_cmp_eq_u32 s62, 12
	s_cselect_b32 s41, s21, s39
	s_cselect_b32 s40, s58, s38
	s_cselect_b32 s39, s19, s61
	s_cselect_b32 s38, s59, s60
	v_lshl_add_u64 v[192:193], s[36:37], 0, v[136:137]
	s_add_i32 m0, s27, 0xc000
	ds_read_b128 v[184:187], v149
	ds_read_b128 v[188:191], v149 offset:1024
	ds_read_b128 v[196:199], v149 offset:2048
	ds_read_b128 v[200:203], v149 offset:3072
	ds_read_b128 v[204:207], v149 offset:4096
	ds_read_b128 v[208:211], v149 offset:5120
	ds_read_b128 v[212:215], v149 offset:6144
	ds_read_b128 v[216:219], v149 offset:7168
	global_load_lds_dwordx4 v[192:193], off
	v_lshl_add_u64 v[192:193], s[36:37], 0, v[138:139]
	s_add_i32 m0, s27, 0xe000
	s_nop 0
	global_load_lds_dwordx4 v[192:193], off
	s_waitcnt vmcnt(8)
	s_waitcnt lgkmcnt(0)
	s_barrier
	s_setprio 1
	s_waitcnt lgkmcnt(0)
	v_mfma_f32_16x16x32_bf16 v[124:127], v[150:153], v[184:187], 0
	v_mfma_f32_16x16x32_bf16 v[120:123], v[158:161], v[184:187], 0
	v_mfma_f32_16x16x32_bf16 v[108:111], v[150:153], v[196:199], 0
	v_mfma_f32_16x16x32_bf16 v[104:107], v[158:161], v[196:199], 0
	v_mfma_f32_16x16x32_bf16 v[92:95], v[150:153], v[204:207], 0
	v_mfma_f32_16x16x32_bf16 v[88:91], v[158:161], v[204:207], 0
	v_mfma_f32_16x16x32_bf16 v[76:79], v[150:153], v[212:215], 0
	v_mfma_f32_16x16x32_bf16 v[72:75], v[158:161], v[212:215], 0
	v_mfma_f32_16x16x32_bf16 v[124:127], v[154:157], v[188:191], v[124:127]
	v_mfma_f32_16x16x32_bf16 v[120:123], v[162:165], v[188:191], v[120:123]
	v_mfma_f32_16x16x32_bf16 v[108:111], v[154:157], v[200:203], v[108:111]
	v_mfma_f32_16x16x32_bf16 v[104:107], v[162:165], v[200:203], v[104:107]
	v_mfma_f32_16x16x32_bf16 v[92:95], v[154:157], v[208:211], v[92:95]
	v_mfma_f32_16x16x32_bf16 v[88:91], v[162:165], v[208:211], v[88:91]
	v_mfma_f32_16x16x32_bf16 v[76:79], v[154:157], v[216:219], v[76:79]
	v_mfma_f32_16x16x32_bf16 v[72:75], v[162:165], v[216:219], v[72:75]
	s_setprio 0
	s_setprio 1
	v_mfma_f32_16x16x32_bf16 v[116:119], v[166:169], v[184:187], 0
	v_mfma_f32_16x16x32_bf16 v[112:115], v[174:177], v[184:187], 0
	v_mfma_f32_16x16x32_bf16 v[100:103], v[166:169], v[196:199], 0
	v_mfma_f32_16x16x32_bf16 v[96:99], v[174:177], v[196:199], 0
	v_mfma_f32_16x16x32_bf16 v[84:87], v[166:169], v[204:207], 0
	v_mfma_f32_16x16x32_bf16 v[80:83], v[174:177], v[204:207], 0
	v_mfma_f32_16x16x32_bf16 v[68:71], v[166:169], v[212:215], 0
	v_mfma_f32_16x16x32_bf16 v[64:67], v[174:177], v[212:215], 0
	v_mfma_f32_16x16x32_bf16 v[116:119], v[170:173], v[188:191], v[116:119]
	v_mfma_f32_16x16x32_bf16 v[112:115], v[178:181], v[188:191], v[112:115]
	v_mfma_f32_16x16x32_bf16 v[100:103], v[170:173], v[200:203], v[100:103]
	v_mfma_f32_16x16x32_bf16 v[96:99], v[178:181], v[200:203], v[96:99]
	v_mfma_f32_16x16x32_bf16 v[84:87], v[170:173], v[208:211], v[84:87]
	v_mfma_f32_16x16x32_bf16 v[80:83], v[178:181], v[208:211], v[80:83]
	v_mfma_f32_16x16x32_bf16 v[68:71], v[170:173], v[216:219], v[68:71]
	v_mfma_f32_16x16x32_bf16 v[64:67], v[178:181], v[216:219], v[64:67]
	s_setprio 0
	s_barrier
	s_add_i32 s63, s54, s45
	v_lshl_add_u64 v[192:193], s[38:39], 0, v[130:131]
	s_mov_b32 m0, s63
	ds_read_b128 v[184:187], v149 offset:16384
	ds_read_b128 v[188:191], v149 offset:17408
	ds_read_b128 v[196:199], v149 offset:18432
	ds_read_b128 v[200:203], v149 offset:19456
	ds_read_b128 v[204:207], v149 offset:20480
	ds_read_b128 v[208:211], v149 offset:21504
	ds_read_b128 v[212:215], v149 offset:22528
	ds_read_b128 v[216:219], v149 offset:23552
	global_load_lds_dwordx4 v[192:193], off
	s_add_i32 m0, s63, 0x2000
	s_add_u32 s64, s38, 0x40000
	v_lshl_add_u64 v[220:221], s[38:39], 0, v[134:135]
	s_addc_u32 s65, s39, 0
	s_add_i32 s63, s55, s45
	global_load_lds_dwordx4 v[220:221], off
	v_lshl_add_u64 v[222:223], s[64:65], 0, v[130:131]
	s_mov_b32 m0, s63
	v_lshl_add_u64 v[224:225], s[40:41], 0, v[132:133]
	global_load_lds_dwordx4 v[222:223], off
	v_lshl_add_u64 v[222:223], s[64:65], 0, v[134:135]
	s_add_i32 m0, s63, 0x2000
	s_nop 0
	global_load_lds_dwordx4 v[222:223], off
	v_lshl_add_u64 v[222:223], s[40:41], 0, v[128:129]
	s_mov_b32 m0, s27
	s_nop 0
	global_load_lds_dwordx4 v[222:223], off
	s_mov_b32 m0, s46
	s_nop 0
	global_load_lds_dwordx4 v[224:225], off
	s_waitcnt vmcnt(8)
	s_waitcnt lgkmcnt(0)
	s_barrier
	s_setprio 1
	s_waitcnt lgkmcnt(0)
	v_mfma_f32_16x16x32_bf16 v[60:63], v[150:153], v[184:187], 0
	v_mfma_f32_16x16x32_bf16 v[56:59], v[158:161], v[184:187], 0
	v_mfma_f32_16x16x32_bf16 v[44:47], v[150:153], v[196:199], 0
	v_mfma_f32_16x16x32_bf16 v[40:43], v[158:161], v[196:199], 0
	v_mfma_f32_16x16x32_bf16 v[28:31], v[150:153], v[204:207], 0
	v_mfma_f32_16x16x32_bf16 v[24:27], v[158:161], v[204:207], 0
	v_mfma_f32_16x16x32_bf16 v[12:15], v[150:153], v[212:215], 0
	v_mfma_f32_16x16x32_bf16 v[8:11], v[158:161], v[212:215], 0
	v_mfma_f32_16x16x32_bf16 v[60:63], v[154:157], v[188:191], v[60:63]
	v_mfma_f32_16x16x32_bf16 v[56:59], v[162:165], v[188:191], v[56:59]
	v_mfma_f32_16x16x32_bf16 v[44:47], v[154:157], v[200:203], v[44:47]
	v_mfma_f32_16x16x32_bf16 v[40:43], v[162:165], v[200:203], v[40:43]
	v_mfma_f32_16x16x32_bf16 v[28:31], v[154:157], v[208:211], v[28:31]
	v_mfma_f32_16x16x32_bf16 v[24:27], v[162:165], v[208:211], v[24:27]
	v_mfma_f32_16x16x32_bf16 v[12:15], v[154:157], v[216:219], v[12:15]
	v_mfma_f32_16x16x32_bf16 v[8:11], v[162:165], v[216:219], v[8:11]
	s_setprio 0
	s_setprio 1
	v_mfma_f32_16x16x32_bf16 v[52:55], v[166:169], v[184:187], 0
	v_mfma_f32_16x16x32_bf16 v[48:51], v[174:177], v[184:187], 0
	v_mfma_f32_16x16x32_bf16 v[36:39], v[166:169], v[196:199], 0
	v_mfma_f32_16x16x32_bf16 v[32:35], v[174:177], v[196:199], 0
	v_mfma_f32_16x16x32_bf16 v[20:23], v[166:169], v[204:207], 0
	v_mfma_f32_16x16x32_bf16 v[16:19], v[174:177], v[204:207], 0
	v_mfma_f32_16x16x32_bf16 v[4:7], v[166:169], v[212:215], 0
	v_mfma_f32_16x16x32_bf16 v[0:3], v[174:177], v[212:215], 0
	v_mfma_f32_16x16x32_bf16 v[52:55], v[170:173], v[188:191], v[52:55]
	v_mfma_f32_16x16x32_bf16 v[48:51], v[178:181], v[188:191], v[48:51]
	v_mfma_f32_16x16x32_bf16 v[36:39], v[170:173], v[200:203], v[36:39]
	v_mfma_f32_16x16x32_bf16 v[32:35], v[178:181], v[200:203], v[32:35]
	v_mfma_f32_16x16x32_bf16 v[20:23], v[170:173], v[208:211], v[20:23]
	v_mfma_f32_16x16x32_bf16 v[16:19], v[178:181], v[208:211], v[16:19]
	v_mfma_f32_16x16x32_bf16 v[4:7], v[170:173], v[216:219], v[4:7]
	v_mfma_f32_16x16x32_bf16 v[0:3], v[178:181], v[216:219], v[0:3]
	s_setprio 0
	s_barrier
	s_add_i32 s63, 0, 0x18000
	s_add_i32 s64, 0, 0x1c000
	v_add_u32_e32 v162, s63, v145
	v_add_u32_e32 v178, s64, v145
	ds_read_b128 v[150:153], v162
	ds_read_b128 v[154:157], v162 offset:1024
	ds_read_b128 v[158:161], v162 offset:2048
	ds_read_b128 v[162:165], v162 offset:3072
	ds_read_b128 v[166:169], v178
	ds_read_b128 v[170:173], v178 offset:1024
	ds_read_b128 v[174:177], v178 offset:2048
	ds_read_b128 v[178:181], v178 offset:3072
	s_add_u32 s40, s40, 0x40000
	s_addc_u32 s41, s41, 0
	s_mov_b32 m0, s47
	v_lshl_add_u64 v[226:227], s[40:41], 0, v[128:129]
	ds_read_b128 v[184:187], v149 offset:32768
	ds_read_b128 v[188:191], v149 offset:33792
	ds_read_b128 v[196:199], v149 offset:34816
	ds_read_b128 v[200:203], v149 offset:35840
	ds_read_b128 v[204:207], v149 offset:36864
	ds_read_b128 v[208:211], v149 offset:37888
	ds_read_b128 v[212:215], v149 offset:38912
	ds_read_b128 v[216:219], v149 offset:39936
	global_load_lds_dwordx4 v[226:227], off
	v_lshl_add_u64 v[226:227], s[40:41], 0, v[132:133]
	s_mov_b32 m0, s48
	s_nop 0
	global_load_lds_dwordx4 v[226:227], off
	s_waitcnt vmcnt(8)
	s_waitcnt lgkmcnt(0)
	s_barrier
	s_setprio 1
	s_waitcnt lgkmcnt(0)
	v_mfma_f32_16x16x32_bf16 v[124:127], v[150:153], v[184:187], v[124:127]
	v_mfma_f32_16x16x32_bf16 v[120:123], v[158:161], v[184:187], v[120:123]
	v_mfma_f32_16x16x32_bf16 v[108:111], v[150:153], v[196:199], v[108:111]
	v_mfma_f32_16x16x32_bf16 v[104:107], v[158:161], v[196:199], v[104:107]
	v_mfma_f32_16x16x32_bf16 v[92:95], v[150:153], v[204:207], v[92:95]
	v_mfma_f32_16x16x32_bf16 v[88:91], v[158:161], v[204:207], v[88:91]
	v_mfma_f32_16x16x32_bf16 v[76:79], v[150:153], v[212:215], v[76:79]
	v_mfma_f32_16x16x32_bf16 v[72:75], v[158:161], v[212:215], v[72:75]
	v_mfma_f32_16x16x32_bf16 v[124:127], v[154:157], v[188:191], v[124:127]
	v_mfma_f32_16x16x32_bf16 v[120:123], v[162:165], v[188:191], v[120:123]
	v_mfma_f32_16x16x32_bf16 v[108:111], v[154:157], v[200:203], v[108:111]
	v_mfma_f32_16x16x32_bf16 v[104:107], v[162:165], v[200:203], v[104:107]
	v_mfma_f32_16x16x32_bf16 v[92:95], v[154:157], v[208:211], v[92:95]
	v_mfma_f32_16x16x32_bf16 v[88:91], v[162:165], v[208:211], v[88:91]
	v_mfma_f32_16x16x32_bf16 v[76:79], v[154:157], v[216:219], v[76:79]
	v_mfma_f32_16x16x32_bf16 v[72:75], v[162:165], v[216:219], v[72:75]
	s_setprio 0
	s_setprio 1
	v_mfma_f32_16x16x32_bf16 v[116:119], v[166:169], v[184:187], v[116:119]
	v_mfma_f32_16x16x32_bf16 v[112:115], v[174:177], v[184:187], v[112:115]
	v_mfma_f32_16x16x32_bf16 v[100:103], v[166:169], v[196:199], v[100:103]
	v_mfma_f32_16x16x32_bf16 v[96:99], v[174:177], v[196:199], v[96:99]
	v_mfma_f32_16x16x32_bf16 v[84:87], v[166:169], v[204:207], v[84:87]
	v_mfma_f32_16x16x32_bf16 v[80:83], v[174:177], v[204:207], v[80:83]
	v_mfma_f32_16x16x32_bf16 v[68:71], v[166:169], v[212:215], v[68:71]
	v_mfma_f32_16x16x32_bf16 v[64:67], v[174:177], v[212:215], v[64:67]
	v_mfma_f32_16x16x32_bf16 v[116:119], v[170:173], v[188:191], v[116:119]
	v_mfma_f32_16x16x32_bf16 v[112:115], v[178:181], v[188:191], v[112:115]
	v_mfma_f32_16x16x32_bf16 v[100:103], v[170:173], v[200:203], v[100:103]
	v_mfma_f32_16x16x32_bf16 v[96:99], v[178:181], v[200:203], v[96:99]
	v_mfma_f32_16x16x32_bf16 v[84:87], v[170:173], v[208:211], v[84:87]
	v_mfma_f32_16x16x32_bf16 v[80:83], v[178:181], v[208:211], v[80:83]
	v_mfma_f32_16x16x32_bf16 v[68:71], v[170:173], v[216:219], v[68:71]
	v_mfma_f32_16x16x32_bf16 v[64:67], v[178:181], v[216:219], v[64:67]
	s_setprio 0
	s_barrier
	s_add_i32 s40, s63, s45
	v_lshl_add_u64 v[192:193], v[192:193], 0, s[14:15]
	s_mov_b32 m0, s40
	ds_read_b128 v[184:187], v149 offset:49152
	ds_read_b128 v[188:191], v149 offset:50176
	ds_read_b128 v[196:199], v149 offset:51200
	ds_read_b128 v[200:203], v149 offset:52224
	ds_read_b128 v[204:207], v149 offset:53248
	ds_read_b128 v[208:211], v149 offset:54272
	ds_read_b128 v[212:215], v149 offset:55296
	ds_read_b128 v[216:219], v149 offset:56320
	global_load_lds_dwordx4 v[192:193], off
	s_add_i32 m0, s40, 0x2000
	s_add_u32 s38, s38, 0x40080
	v_lshl_add_u64 v[192:193], v[220:221], 0, s[14:15]
	s_addc_u32 s39, s39, 0
	s_add_i32 s40, s64, s45
	global_load_lds_dwordx4 v[192:193], off
	v_lshl_add_u64 v[192:193], s[38:39], 0, v[130:131]
	s_mov_b32 m0, s40
	s_nop 0
	global_load_lds_dwordx4 v[192:193], off
	v_lshl_add_u64 v[192:193], s[38:39], 0, v[134:135]
	s_add_i32 m0, s40, 0x2000
	s_nop 0
	global_load_lds_dwordx4 v[192:193], off
	v_lshl_add_u64 v[192:193], v[222:223], 0, s[14:15]
	s_mov_b32 m0, s50
	s_nop 0
	global_load_lds_dwordx4 v[192:193], off
	v_lshl_add_u64 v[192:193], v[224:225], 0, s[14:15]
	s_mov_b32 m0, s51
	s_nop 0
	global_load_lds_dwordx4 v[192:193], off
	s_waitcnt vmcnt(8)
	s_waitcnt lgkmcnt(0)
	s_barrier
	s_setprio 1
	s_waitcnt lgkmcnt(0)
	v_mfma_f32_16x16x32_bf16 v[60:63], v[150:153], v[184:187], v[60:63]
	v_mfma_f32_16x16x32_bf16 v[56:59], v[158:161], v[184:187], v[56:59]
	v_mfma_f32_16x16x32_bf16 v[44:47], v[150:153], v[196:199], v[44:47]
	v_mfma_f32_16x16x32_bf16 v[40:43], v[158:161], v[196:199], v[40:43]
	v_mfma_f32_16x16x32_bf16 v[28:31], v[150:153], v[204:207], v[28:31]
	v_mfma_f32_16x16x32_bf16 v[24:27], v[158:161], v[204:207], v[24:27]
	v_mfma_f32_16x16x32_bf16 v[12:15], v[150:153], v[212:215], v[12:15]
	v_mfma_f32_16x16x32_bf16 v[8:11], v[158:161], v[212:215], v[8:11]
	v_mfma_f32_16x16x32_bf16 v[60:63], v[154:157], v[188:191], v[60:63]
	v_mfma_f32_16x16x32_bf16 v[56:59], v[162:165], v[188:191], v[56:59]
	v_mfma_f32_16x16x32_bf16 v[44:47], v[154:157], v[200:203], v[44:47]
	v_mfma_f32_16x16x32_bf16 v[40:43], v[162:165], v[200:203], v[40:43]
	v_mfma_f32_16x16x32_bf16 v[28:31], v[154:157], v[208:211], v[28:31]
	v_mfma_f32_16x16x32_bf16 v[24:27], v[162:165], v[208:211], v[24:27]
	v_mfma_f32_16x16x32_bf16 v[12:15], v[154:157], v[216:219], v[12:15]
	v_mfma_f32_16x16x32_bf16 v[8:11], v[162:165], v[216:219], v[8:11]
	s_setprio 0
	s_setprio 1
	v_mfma_f32_16x16x32_bf16 v[52:55], v[166:169], v[184:187], v[52:55]
	v_mfma_f32_16x16x32_bf16 v[48:51], v[174:177], v[184:187], v[48:51]
	v_mfma_f32_16x16x32_bf16 v[36:39], v[166:169], v[196:199], v[36:39]
	v_mfma_f32_16x16x32_bf16 v[32:35], v[174:177], v[196:199], v[32:35]
	v_mfma_f32_16x16x32_bf16 v[20:23], v[166:169], v[204:207], v[20:23]
	v_mfma_f32_16x16x32_bf16 v[16:19], v[174:177], v[204:207], v[16:19]
	v_mfma_f32_16x16x32_bf16 v[4:7], v[166:169], v[212:215], v[4:7]
	v_mfma_f32_16x16x32_bf16 v[0:3], v[174:177], v[212:215], v[0:3]
	v_mfma_f32_16x16x32_bf16 v[52:55], v[170:173], v[188:191], v[52:55]
	v_mfma_f32_16x16x32_bf16 v[48:51], v[178:181], v[188:191], v[48:51]
	v_mfma_f32_16x16x32_bf16 v[36:39], v[170:173], v[200:203], v[36:39]
	v_mfma_f32_16x16x32_bf16 v[32:35], v[178:181], v[200:203], v[32:35]
	v_mfma_f32_16x16x32_bf16 v[20:23], v[170:173], v[208:211], v[20:23]
	v_mfma_f32_16x16x32_bf16 v[16:19], v[178:181], v[208:211], v[16:19]
	v_mfma_f32_16x16x32_bf16 v[4:7], v[170:173], v[216:219], v[4:7]
	v_mfma_f32_16x16x32_bf16 v[0:3], v[178:181], v[216:219], v[0:3]
	s_setprio 0
	s_barrier
	s_add_i32 s62, s62, 2
	s_add_u32 s36, s36, 0x100
	s_addc_u32 s37, s37, 0
	s_add_u32 s60, s60, 0x100
	s_addc_u32 s61, s61, 0
	s_cmp_gt_u32 s62, 13
	s_cbranch_scc0 .LBB0_1574
	s_branch .Lkpeel_done_1574

.LBB0_1645:
	s_add_u32 s67, s42, 0x100
	s_addc_u32 s68, s43, 0
	s_mov_b32 s69, -2
	ds_read_b128 v[128:131], v159
	ds_read_b128 v[148:151], v159 offset:1024
	ds_read_b128 v[152:155], v159 offset:2048
	ds_read_b128 v[162:165], v159 offset:3072
	ds_read_b128 v[166:169], v160
	ds_read_b128 v[170:173], v160 offset:1024
	ds_read_b128 v[174:177], v160 offset:2048
	ds_read_b128 v[178:181], v160 offset:3072
	s_add_u32 s42, s40, 0x100
	s_addc_u32 s43, s41, 0
	s_cmp_eq_u32 s69, 40
	s_cselect_b32 s47, s7, s43
	s_cselect_b32 s46, s6, s42
	s_cselect_b32 s45, s39, s68
	s_cselect_b32 s44, s38, s67
	v_lshl_add_u64 v[192:193], s[40:41], 0, v[140:141]
	s_add_i32 m0, s52, 0xc000
	ds_read_b128 v[184:187], v161
	ds_read_b128 v[188:191], v161 offset:1024
	ds_read_b128 v[196:199], v161 offset:2048
	ds_read_b128 v[200:203], v161 offset:3072
	ds_read_b128 v[204:207], v161 offset:4096
	ds_read_b128 v[208:211], v161 offset:5120
	ds_read_b128 v[212:215], v161 offset:6144
	ds_read_b128 v[216:219], v161 offset:7168
	global_load_lds_dwordx4 v[192:193], off
	v_lshl_add_u64 v[192:193], s[40:41], 0, v[142:143]
	s_add_i32 m0, s52, 0xe000
	s_nop 0
	global_load_lds_dwordx4 v[192:193], off
	s_waitcnt vmcnt(8)
	s_waitcnt lgkmcnt(0)
	s_barrier
	s_setprio 1
	s_waitcnt lgkmcnt(0)
	v_mfma_f32_16x16x32_bf16 v[124:127], v[128:131], v[184:187], 0
	v_mfma_f32_16x16x32_bf16 v[120:123], v[152:155], v[184:187], 0
	v_mfma_f32_16x16x32_bf16 v[116:119], v[128:131], v[196:199], 0
	v_mfma_f32_16x16x32_bf16 v[112:115], v[152:155], v[196:199], 0
	v_mfma_f32_16x16x32_bf16 v[96:99], v[128:131], v[204:207], 0
	v_mfma_f32_16x16x32_bf16 v[88:91], v[152:155], v[204:207], 0
	v_mfma_f32_16x16x32_bf16 v[80:83], v[128:131], v[212:215], 0
	v_mfma_f32_16x16x32_bf16 v[72:75], v[152:155], v[212:215], 0
	v_mfma_f32_16x16x32_bf16 v[124:127], v[148:151], v[188:191], v[124:127]
	v_mfma_f32_16x16x32_bf16 v[120:123], v[162:165], v[188:191], v[120:123]
	v_mfma_f32_16x16x32_bf16 v[116:119], v[148:151], v[200:203], v[116:119]
	v_mfma_f32_16x16x32_bf16 v[112:115], v[162:165], v[200:203], v[112:115]
	v_mfma_f32_16x16x32_bf16 v[96:99], v[148:151], v[208:211], v[96:99]
	v_mfma_f32_16x16x32_bf16 v[88:91], v[162:165], v[208:211], v[88:91]
	v_mfma_f32_16x16x32_bf16 v[80:83], v[148:151], v[216:219], v[80:83]
	v_mfma_f32_16x16x32_bf16 v[72:75], v[162:165], v[216:219], v[72:75]
	s_setprio 0
	s_setprio 1
	v_mfma_f32_16x16x32_bf16 v[108:111], v[166:169], v[184:187], 0
	v_mfma_f32_16x16x32_bf16 v[104:107], v[174:177], v[184:187], 0
	v_mfma_f32_16x16x32_bf16 v[100:103], v[166:169], v[196:199], 0
	v_mfma_f32_16x16x32_bf16 v[92:95], v[174:177], v[196:199], 0
	v_mfma_f32_16x16x32_bf16 v[84:87], v[166:169], v[204:207], 0
	v_mfma_f32_16x16x32_bf16 v[76:79], v[174:177], v[204:207], 0
	v_mfma_f32_16x16x32_bf16 v[68:71], v[166:169], v[212:215], 0
	v_mfma_f32_16x16x32_bf16 v[64:67], v[174:177], v[212:215], 0
	v_mfma_f32_16x16x32_bf16 v[108:111], v[170:173], v[188:191], v[108:111]
	v_mfma_f32_16x16x32_bf16 v[104:107], v[178:181], v[188:191], v[104:107]
	v_mfma_f32_16x16x32_bf16 v[100:103], v[170:173], v[200:203], v[100:103]
	v_mfma_f32_16x16x32_bf16 v[92:95], v[178:181], v[200:203], v[92:95]
	v_mfma_f32_16x16x32_bf16 v[84:87], v[170:173], v[208:211], v[84:87]
	v_mfma_f32_16x16x32_bf16 v[76:79], v[178:181], v[208:211], v[76:79]
	v_mfma_f32_16x16x32_bf16 v[68:71], v[170:173], v[216:219], v[68:71]
	v_mfma_f32_16x16x32_bf16 v[64:67], v[178:181], v[216:219], v[64:67]
	s_setprio 0
	s_barrier
	s_add_i32 s40, s61, s49
	v_lshl_add_u64 v[192:193], s[44:45], 0, v[136:137]
	s_mov_b32 m0, s40
	ds_read_b128 v[184:187], v161 offset:16384
	ds_read_b128 v[188:191], v161 offset:17408
	ds_read_b128 v[196:199], v161 offset:18432
	ds_read_b128 v[200:203], v161 offset:19456
	ds_read_b128 v[204:207], v161 offset:20480
	ds_read_b128 v[208:211], v161 offset:21504
	ds_read_b128 v[212:215], v161 offset:22528
	ds_read_b128 v[216:219], v161 offset:23552
	global_load_lds_dwordx4 v[192:193], off
	s_add_i32 m0, s40, 0x2000
	s_add_u32 s40, s44, 0xb0000
	v_lshl_add_u64 v[220:221], s[44:45], 0, v[132:133]
	s_addc_u32 s41, s45, 0
	s_add_i32 s70, s62, s49
	global_load_lds_dwordx4 v[220:221], off
	v_lshl_add_u64 v[222:223], s[40:41], 0, v[136:137]
	s_mov_b32 m0, s70
	v_lshl_add_u64 v[224:225], s[46:47], 0, v[134:135]
	global_load_lds_dwordx4 v[222:223], off
	v_lshl_add_u64 v[222:223], s[40:41], 0, v[132:133]
	s_add_i32 m0, s70, 0x2000
	s_nop 0
	global_load_lds_dwordx4 v[222:223], off
	v_lshl_add_u64 v[222:223], s[46:47], 0, v[138:139]
	s_mov_b32 m0, s52
	s_nop 0
	global_load_lds_dwordx4 v[222:223], off
	s_mov_b32 m0, s53
	s_nop 0
	global_load_lds_dwordx4 v[224:225], off
	s_waitcnt vmcnt(8)
	s_waitcnt lgkmcnt(0)
	s_barrier
	s_setprio 1
	s_waitcnt lgkmcnt(0)
	v_mfma_f32_16x16x32_bf16 v[60:63], v[128:131], v[184:187], 0
	v_mfma_f32_16x16x32_bf16 v[56:59], v[152:155], v[184:187], 0
	v_mfma_f32_16x16x32_bf16 v[48:51], v[128:131], v[196:199], 0
	v_mfma_f32_16x16x32_bf16 v[40:43], v[152:155], v[196:199], 0
	v_mfma_f32_16x16x32_bf16 v[32:35], v[128:131], v[204:207], 0
	v_mfma_f32_16x16x32_bf16 v[24:27], v[152:155], v[204:207], 0
	v_mfma_f32_16x16x32_bf16 v[16:19], v[128:131], v[212:215], 0
	v_mfma_f32_16x16x32_bf16 v[8:11], v[152:155], v[212:215], 0
	v_mfma_f32_16x16x32_bf16 v[60:63], v[148:151], v[188:191], v[60:63]
	v_mfma_f32_16x16x32_bf16 v[56:59], v[162:165], v[188:191], v[56:59]
	v_mfma_f32_16x16x32_bf16 v[48:51], v[148:151], v[200:203], v[48:51]
	v_mfma_f32_16x16x32_bf16 v[40:43], v[162:165], v[200:203], v[40:43]
	v_mfma_f32_16x16x32_bf16 v[32:35], v[148:151], v[208:211], v[32:35]
	v_mfma_f32_16x16x32_bf16 v[24:27], v[162:165], v[208:211], v[24:27]
	v_mfma_f32_16x16x32_bf16 v[16:19], v[148:151], v[216:219], v[16:19]
	v_mfma_f32_16x16x32_bf16 v[8:11], v[162:165], v[216:219], v[8:11]
	s_setprio 0
	s_setprio 1
	v_mfma_f32_16x16x32_bf16 v[52:55], v[166:169], v[184:187], 0
	v_mfma_f32_16x16x32_bf16 v[44:47], v[174:177], v[184:187], 0
	v_mfma_f32_16x16x32_bf16 v[36:39], v[166:169], v[196:199], 0
	v_mfma_f32_16x16x32_bf16 v[28:31], v[174:177], v[196:199], 0
	v_mfma_f32_16x16x32_bf16 v[20:23], v[166:169], v[204:207], 0
	v_mfma_f32_16x16x32_bf16 v[12:15], v[174:177], v[204:207], 0
	v_mfma_f32_16x16x32_bf16 v[4:7], v[166:169], v[212:215], 0
	v_mfma_f32_16x16x32_bf16 v[0:3], v[174:177], v[212:215], 0
	v_mfma_f32_16x16x32_bf16 v[52:55], v[170:173], v[188:191], v[52:55]
	v_mfma_f32_16x16x32_bf16 v[44:47], v[178:181], v[188:191], v[44:47]
	v_mfma_f32_16x16x32_bf16 v[36:39], v[170:173], v[200:203], v[36:39]
	v_mfma_f32_16x16x32_bf16 v[28:31], v[178:181], v[200:203], v[28:31]
	v_mfma_f32_16x16x32_bf16 v[20:23], v[170:173], v[208:211], v[20:23]
	v_mfma_f32_16x16x32_bf16 v[12:15], v[178:181], v[208:211], v[12:15]
	v_mfma_f32_16x16x32_bf16 v[4:7], v[170:173], v[216:219], v[4:7]
	v_mfma_f32_16x16x32_bf16 v[0:3], v[178:181], v[216:219], v[0:3]
	s_setprio 0
	s_barrier
	s_add_i32 s70, 0, 0x18000
	s_add_i32 s71, 0, 0x1c000
	v_add_u32_e32 v162, s70, v157
	v_add_u32_e32 v178, s71, v157
	ds_read_b128 v[128:131], v162
	ds_read_b128 v[148:151], v162 offset:1024
	ds_read_b128 v[152:155], v162 offset:2048
	ds_read_b128 v[162:165], v162 offset:3072
	ds_read_b128 v[166:169], v178
	ds_read_b128 v[170:173], v178 offset:1024
	ds_read_b128 v[174:177], v178 offset:2048
	ds_read_b128 v[178:181], v178 offset:3072
	s_add_u32 s40, s46, 0xb0000
	s_addc_u32 s41, s47, 0
	s_mov_b32 m0, s54
	v_lshl_add_u64 v[226:227], s[40:41], 0, v[138:139]
	ds_read_b128 v[184:187], v161 offset:32768
	ds_read_b128 v[188:191], v161 offset:33792
	ds_read_b128 v[196:199], v161 offset:34816
	ds_read_b128 v[200:203], v161 offset:35840
	ds_read_b128 v[204:207], v161 offset:36864
	ds_read_b128 v[208:211], v161 offset:37888
	ds_read_b128 v[212:215], v161 offset:38912
	ds_read_b128 v[216:219], v161 offset:39936
	global_load_lds_dwordx4 v[226:227], off
	v_lshl_add_u64 v[226:227], s[40:41], 0, v[134:135]
	s_mov_b32 m0, s55
	s_nop 0
	global_load_lds_dwordx4 v[226:227], off
	s_waitcnt vmcnt(8)
	s_waitcnt lgkmcnt(0)
	s_barrier
	s_setprio 1
	s_waitcnt lgkmcnt(0)
	v_mfma_f32_16x16x32_bf16 v[124:127], v[128:131], v[184:187], v[124:127]
	v_mfma_f32_16x16x32_bf16 v[120:123], v[152:155], v[184:187], v[120:123]
	v_mfma_f32_16x16x32_bf16 v[116:119], v[128:131], v[196:199], v[116:119]
	v_mfma_f32_16x16x32_bf16 v[112:115], v[152:155], v[196:199], v[112:115]
	v_mfma_f32_16x16x32_bf16 v[96:99], v[128:131], v[204:207], v[96:99]
	v_mfma_f32_16x16x32_bf16 v[88:91], v[152:155], v[204:207], v[88:91]
	v_mfma_f32_16x16x32_bf16 v[80:83], v[128:131], v[212:215], v[80:83]
	v_mfma_f32_16x16x32_bf16 v[72:75], v[152:155], v[212:215], v[72:75]
	v_mfma_f32_16x16x32_bf16 v[124:127], v[148:151], v[188:191], v[124:127]
	v_mfma_f32_16x16x32_bf16 v[120:123], v[162:165], v[188:191], v[120:123]
	v_mfma_f32_16x16x32_bf16 v[116:119], v[148:151], v[200:203], v[116:119]
	v_mfma_f32_16x16x32_bf16 v[112:115], v[162:165], v[200:203], v[112:115]
	v_mfma_f32_16x16x32_bf16 v[96:99], v[148:151], v[208:211], v[96:99]
	v_mfma_f32_16x16x32_bf16 v[88:91], v[162:165], v[208:211], v[88:91]
	v_mfma_f32_16x16x32_bf16 v[80:83], v[148:151], v[216:219], v[80:83]
	v_mfma_f32_16x16x32_bf16 v[72:75], v[162:165], v[216:219], v[72:75]
	s_setprio 0
	s_setprio 1
	v_mfma_f32_16x16x32_bf16 v[108:111], v[166:169], v[184:187], v[108:111]
	v_mfma_f32_16x16x32_bf16 v[104:107], v[174:177], v[184:187], v[104:107]
	v_mfma_f32_16x16x32_bf16 v[100:103], v[166:169], v[196:199], v[100:103]
	v_mfma_f32_16x16x32_bf16 v[92:95], v[174:177], v[196:199], v[92:95]
	v_mfma_f32_16x16x32_bf16 v[84:87], v[166:169], v[204:207], v[84:87]
	v_mfma_f32_16x16x32_bf16 v[76:79], v[174:177], v[204:207], v[76:79]
	v_mfma_f32_16x16x32_bf16 v[68:71], v[166:169], v[212:215], v[68:71]
	v_mfma_f32_16x16x32_bf16 v[64:67], v[174:177], v[212:215], v[64:67]
	v_mfma_f32_16x16x32_bf16 v[108:111], v[170:173], v[188:191], v[108:111]
	v_mfma_f32_16x16x32_bf16 v[104:107], v[178:181], v[188:191], v[104:107]
	v_mfma_f32_16x16x32_bf16 v[100:103], v[170:173], v[200:203], v[100:103]
	v_mfma_f32_16x16x32_bf16 v[92:95], v[178:181], v[200:203], v[92:95]
	v_mfma_f32_16x16x32_bf16 v[84:87], v[170:173], v[208:211], v[84:87]
	v_mfma_f32_16x16x32_bf16 v[76:79], v[178:181], v[208:211], v[76:79]
	v_mfma_f32_16x16x32_bf16 v[68:71], v[170:173], v[216:219], v[68:71]
	v_mfma_f32_16x16x32_bf16 v[64:67], v[178:181], v[216:219], v[64:67]
	s_setprio 0
	s_barrier
	s_add_i32 s40, s70, s49
	v_lshl_add_u64 v[192:193], v[192:193], 0, s[16:17]
	s_mov_b32 m0, s40
	ds_read_b128 v[184:187], v161 offset:49152
	ds_read_b128 v[188:191], v161 offset:50176
	ds_read_b128 v[196:199], v161 offset:51200
	ds_read_b128 v[200:203], v161 offset:52224
	ds_read_b128 v[204:207], v161 offset:53248
	ds_read_b128 v[208:211], v161 offset:54272
	ds_read_b128 v[212:215], v161 offset:55296
	ds_read_b128 v[216:219], v161 offset:56320
	global_load_lds_dwordx4 v[192:193], off
	s_add_i32 m0, s40, 0x2000
	s_add_u32 s40, s44, 0xb0080
	v_lshl_add_u64 v[192:193], v[220:221], 0, s[16:17]
	s_addc_u32 s41, s45, 0
	s_add_i32 s44, s71, s49
	global_load_lds_dwordx4 v[192:193], off
	v_lshl_add_u64 v[192:193], s[40:41], 0, v[136:137]
	s_mov_b32 m0, s44
	s_nop 0
	global_load_lds_dwordx4 v[192:193], off
	v_lshl_add_u64 v[192:193], s[40:41], 0, v[132:133]
	s_add_i32 m0, s44, 0x2000
	s_nop 0
	global_load_lds_dwordx4 v[192:193], off
	v_lshl_add_u64 v[192:193], v[222:223], 0, s[16:17]
	s_mov_b32 m0, s57
	s_nop 0
	global_load_lds_dwordx4 v[192:193], off
	v_lshl_add_u64 v[192:193], v[224:225], 0, s[16:17]
	s_mov_b32 m0, s58
	s_nop 0
	global_load_lds_dwordx4 v[192:193], off
	s_waitcnt vmcnt(8)
	s_waitcnt lgkmcnt(0)
	s_barrier
	s_setprio 1
	s_waitcnt lgkmcnt(0)
	v_mfma_f32_16x16x32_bf16 v[60:63], v[128:131], v[184:187], v[60:63]
	v_mfma_f32_16x16x32_bf16 v[56:59], v[152:155], v[184:187], v[56:59]
	v_mfma_f32_16x16x32_bf16 v[48:51], v[128:131], v[196:199], v[48:51]
	v_mfma_f32_16x16x32_bf16 v[40:43], v[152:155], v[196:199], v[40:43]
	v_mfma_f32_16x16x32_bf16 v[32:35], v[128:131], v[204:207], v[32:35]
	v_mfma_f32_16x16x32_bf16 v[24:27], v[152:155], v[204:207], v[24:27]
	v_mfma_f32_16x16x32_bf16 v[16:19], v[128:131], v[212:215], v[16:19]
	v_mfma_f32_16x16x32_bf16 v[8:11], v[152:155], v[212:215], v[8:11]
	v_mfma_f32_16x16x32_bf16 v[60:63], v[148:151], v[188:191], v[60:63]
	v_mfma_f32_16x16x32_bf16 v[56:59], v[162:165], v[188:191], v[56:59]
	v_mfma_f32_16x16x32_bf16 v[48:51], v[148:151], v[200:203], v[48:51]
	v_mfma_f32_16x16x32_bf16 v[40:43], v[162:165], v[200:203], v[40:43]
	v_mfma_f32_16x16x32_bf16 v[32:35], v[148:151], v[208:211], v[32:35]
	v_mfma_f32_16x16x32_bf16 v[24:27], v[162:165], v[208:211], v[24:27]
	v_mfma_f32_16x16x32_bf16 v[16:19], v[148:151], v[216:219], v[16:19]
	v_mfma_f32_16x16x32_bf16 v[8:11], v[162:165], v[216:219], v[8:11]
	s_setprio 0
	s_setprio 1
	v_mfma_f32_16x16x32_bf16 v[52:55], v[166:169], v[184:187], v[52:55]
	v_mfma_f32_16x16x32_bf16 v[44:47], v[174:177], v[184:187], v[44:47]
	v_mfma_f32_16x16x32_bf16 v[36:39], v[166:169], v[196:199], v[36:39]
	v_mfma_f32_16x16x32_bf16 v[28:31], v[174:177], v[196:199], v[28:31]
	v_mfma_f32_16x16x32_bf16 v[20:23], v[166:169], v[204:207], v[20:23]
	v_mfma_f32_16x16x32_bf16 v[12:15], v[174:177], v[204:207], v[12:15]
	v_mfma_f32_16x16x32_bf16 v[4:7], v[166:169], v[212:215], v[4:7]
	v_mfma_f32_16x16x32_bf16 v[0:3], v[174:177], v[212:215], v[0:3]
	v_mfma_f32_16x16x32_bf16 v[52:55], v[170:173], v[188:191], v[52:55]
	v_mfma_f32_16x16x32_bf16 v[44:47], v[178:181], v[188:191], v[44:47]
	v_mfma_f32_16x16x32_bf16 v[36:39], v[170:173], v[200:203], v[36:39]
	v_mfma_f32_16x16x32_bf16 v[28:31], v[178:181], v[200:203], v[28:31]
	v_mfma_f32_16x16x32_bf16 v[20:23], v[170:173], v[208:211], v[20:23]
	v_mfma_f32_16x16x32_bf16 v[12:15], v[178:181], v[208:211], v[12:15]
	v_mfma_f32_16x16x32_bf16 v[4:7], v[170:173], v[216:219], v[4:7]
	v_mfma_f32_16x16x32_bf16 v[0:3], v[178:181], v[216:219], v[0:3]
	s_setprio 0
	s_barrier
	s_add_i32 s69, s69, 2
	s_add_u32 s67, s67, 0x100
	s_addc_u32 s68, s68, 0
	s_cmp_gt_u32 s69, 41
	s_mov_b64 s[40:41], s[42:43]
	s_cbranch_scc0 .LBB0_1646
	s_branch .Lkpeel_done_1646
